# RWKV-7 scan chunk body hand-written: y from new state, DPP wait slots filled, 21 instr per step
# speedup vs baseline: 1.1294x; 1.0365x over previous
; __device__ __forceinline__ void unpack4(uint2 u, float* f) { f[0] = bflo(u.x); f[1] = bfhi(u.x); f[2] = bflo(u.y); f[3] = bfhi(u.y); }
; __device__ __forceinline__ void rwkv_scan_job(const P& p, int job, char* smc) {
;     ...
;   auto stage = [&](RwBuf& bf) {
;     float r[4], rp[4], k[4], kpv[4], v[4], vp[4], ld[4], a[4];
;     unpack4(g_r, r); unpack4(g_rp, rp); unpack4(g_k, k); unpack4(g_kp, kpv); unpack4(g_v, v); unpack4(g_vp, vp);
;     if (g_first) {
; #pragma unroll
;       for (int i = 0; i < 4; i++) { rp[i] = 0.f; kpv[i] = 0.f; vp[i] = 0.f; }
;     }
;     unpack4(g_ld, ld); unpack4(g_a, a);
;     float kkr[4], kpr[4], rs[4], vs[4], ss = 0.f;
; #pragma unroll
;     for (int i = 0; i < 4; i++) {
;       rs[i] = r[i] + (rp[i] - r[i]) * mur[i];
;       float ks = k[i] + (kpv[i] - k[i]) * muk[i];
;       vs[i] = v[i] + (vp[i] - v[i]) * muv[i];
;       kkr[i] = ks * kkc[i];
;       ss += kkr[i] * kkr[i];
;       kpr[i] = ks * (1.f + (a[i] - 1.f) * kac[i]);
;     }
;     ss = sum16(ss);
;     const float inv = rsqrtf(fmaxf(ss, 1e-24f));
;     float c1 = 0.f, c2 = 0.f, c3 = 0.f;
;     float dk[4], kk4[4], kka4[4], wr4[4];
; #pragma unroll
;     for (int i = 0; i < 4; i++) {
;       kk4[i] = kkr[i] * inv;
;       kka4[i] = kk4[i] * a[i];
;       dk[i] = __expf(ld[i]);
;       wr4[i] = dk[i] * rs[i];
;       c1 += kka4[i] * rs[i];
;       c2 += kpr[i] * rs[i];
;       c3 += kpr[i] * rs[i] * rkc[i];
;     }
;     c1 = sum16(c1); c2 = sum16(c2); c3 = sum16(c3);
;     *(float4*)&bf.dec[tl][jg * 4] = make_float4(dk[0], dk[1], dk[2], dk[3]);
;     *(float4*)&bf.kk[tl][jg * 4] = make_float4(kk4[0], kk4[1], kk4[2], kk4[3]);
;     *(float4*)&bf.kka[tl][jg * 4] = make_float4(kka4[0], kka4[1], kka4[2], kka4[3]);
;     *(float4*)&bf.kp[tl][jg * 4] = make_float4(kpr[0], kpr[1], kpr[2], kpr[3]);
;     *(float4*)&bf.wr[tl][jg * 4] = make_float4(wr4[0], wr4[1], wr4[2], wr4[3]);
;     if ((jg >> 2) == rq) *(float4*)&bf.v[tl][(jg & 3) * 4] = make_float4(vs[0], vs[1], vs[2], vs[3]);
;     if (jg == 0) { bf.c[tl][0] = c1; bf.c[tl][1] = c2; if (rq == 0) p.c3buf[(size_t)g_t * 8 + h] = c3; }
;   };
.LBB0_151:
	s_or_b64 exec, exec, s[10:11]
	v_mov_b32_e32 v56, v10
	v_lshlrev_b32_e32 v44, 16, v79
	s_waitcnt vmcnt(1)
	v_lshlrev_b32_e32 v10, 16, v90
	v_and_b32_e32 v50, 0xffff0000, v79
	v_and_b32_e32 v39, 0xffff0000, v90
	v_sub_f32_e32 v37, v37, v44
	v_mul_f32_e32 v10, 0x3fb8aa3b, v10
	v_lshlrev_b32_e32 v42, 16, v78
	v_and_b32_e32 v43, 0xffff0000, v78
	v_lshlrev_b32_e32 v40, 16, v91
	s_waitcnt vmcnt(0)
	v_lshlrev_b32_e32 v52, 16, v92
	v_mul_f32_e32 v60, v14, v37
	v_sub_f32_e32 v37, v38, v50
	v_exp_f32_e32 v38, v10
	v_mul_f32_e32 v10, 0x3fb8aa3b, v39
	v_and_b32_e32 v41, 0xffff0000, v91
	v_and_b32_e32 v54, 0xffff0000, v92
	v_add_f32_e32 v53, -1.0, v52
	v_exp_f32_e32 v39, v10
	v_mul_f32_e32 v10, 0x3fb8aa3b, v40
	v_pk_add_f32 v[34:35], v[34:35], v[42:43] neg_lo:[0,1] neg_hi:[0,1]
	v_lshlrev_b32_e32 v45, 16, v93
	v_and_b32_e32 v51, 0xffff0000, v93
	v_fma_f32 v57, v8, v53, 1.0
	v_add_f32_e32 v53, -1.0, v54
	v_mul_f32_e32 v138, v15, v37
	v_exp_f32_e32 v40, v10
	v_mul_f32_e32 v10, 0x3fb8aa3b, v41
	v_pk_fma_f32 v[34:35], v[12:13], v[34:35], v[42:43]
	v_mov_b32_e32 v61, v139
	v_fma_f32 v59, v9, v53, 1.0
	v_exp_f32_e32 v41, v10
	v_pk_add_f32 v[62:63], v[138:139], v[50:51]
	v_mov_b32_e32 v10, v23
	v_pk_mul_f32 v[42:43], v[20:21], v[34:35]
	v_mov_b32_e32 v53, v34
	v_mov_b32_e32 v55, v35
	v_pk_add_f32 v[34:35], v[60:61], v[44:45]
	v_mov_b32_e32 v23, v56
	v_pk_mul_f32 v[64:65], v[10:11], v[62:63]
	v_pk_mul_f32 v[60:61], v[22:23], v[34:35]
	v_pk_mul_f32 v[66:67], v[42:43], v[42:43]
	v_mov_b32_e32 v68, v64
	v_mov_b32_e32 v69, v60
	v_pk_mul_f32 v[68:69], v[68:69], v[68:69]
	v_add_f32_e32 v37, v66, v67
	v_add_f32_e32 v37, v69, v37
	v_add_f32_e32 v37, v68, v37
	v_readlane_b32 s10, v229, 33
	v_readlane_b32 s11, v229, 34
	v_add_f32_dpp v37, v37, v37 quad_perm:[1,0,3,2] row_mask:0xf bank_mask:0xf bound_ctrl:1
	s_mov_b32 s11, 1.0
	v_mov_b32_e32 v70, v45
	v_add_f32_dpp v37, v37, v37 quad_perm:[2,3,0,1] row_mask:0xf bank_mask:0xf bound_ctrl:1
	v_mov_b32_e32 v71, v34
	v_pk_fma_f32 v[34:35], v[22:23], v[34:35], s[10:11]
	v_add_f32_dpp v37, v37, v37 row_half_mirror row_mask:0xf bank_mask:0xf bound_ctrl:1
	v_pk_mov_b32 v[50:51], v[50:51], v[62:63] op_sel:[1,0]
	v_lshlrev_b32_e32 v114, 8, v24
	v_add_f32_dpp v37, v37, v37 row_mirror row_mask:0xf bank_mask:0xf bound_ctrl:1
	v_max_f32_e32 v37, 0x179abe15, v37
	v_rsq_f32_e32 v140, v37
	v_lshlrev_b32_e32 v46, 16, v76
	v_and_b32_e32 v47, 0xffff0000, v76
	v_lshl_or_b32 v72, v113, 2, v114
	v_pk_mul_f32 v[42:43], v[42:43], v[140:141] op_sel_hi:[1,0]
	v_pk_mul_f32 v[44:45], v[60:61], v[140:141]
	v_mov_b32_e32 v56, v42
	v_mov_b32_e32 v58, v43
	v_pk_mul_f32 v[52:53], v[56:57], v[52:53]
	v_pk_mul_f32 v[54:55], v[58:59], v[54:55]
	v_pk_mul_f32 v[56:57], v[64:65], v[140:141]
	v_pk_fma_f32 v[58:59], v[10:11], v[62:63], s[10:11]
	v_mov_b32_e32 v45, v35
	v_mov_b32_e32 v57, v59
	v_pk_mul_f32 v[34:35], v[44:45], v[70:71]
	v_pk_mul_f32 v[50:51], v[56:57], v[50:51]
	v_mov_b32_e32 v45, v56
	ds_write_b128 v72, v[42:45] offset:4096
	v_mov_b32_e32 v42, v52
	v_mov_b32_e32 v43, v54
	v_mov_b32_e32 v44, v34
	v_mov_b32_e32 v45, v50
	v_pk_add_f32 v[32:33], v[32:33], v[46:47] neg_lo:[0,1] neg_hi:[0,1]
	v_lshlrev_b32_e32 v48, 16, v77
	v_and_b32_e32 v49, 0xffff0000, v77
	ds_write_b128 v72, v[42:45] offset:8192
	v_mov_b32_e32 v42, v53
	v_mov_b32_e32 v43, v55
	v_mov_b32_e32 v44, v35
	v_mov_b32_e32 v45, v51
	v_pk_fma_f32 v[32:33], v[0:1], v[32:33], v[46:47]
	ds_write_b128 v72, v[42:45] offset:12288
	v_pk_mul_f32 v[42:43], v[32:33], v[52:53] op_sel_hi:[0,1]
	v_pk_fma_f32 v[44:45], v[32:33], v[52:53], 0 op_sel_hi:[0,1,0]
	v_pk_add_f32 v[30:31], v[30:31], v[48:49] neg_lo:[0,1] neg_hi:[0,1]
	ds_write_b128 v72, v[38:41]
	v_mov_b32_e32 v38, v32
	v_mov_b32_e32 v39, v33
	v_fma_f32 v37, v16, v43, 0
	v_pk_mul_f32 v[42:43], v[32:33], v[54:55]
	v_pk_fma_f32 v[32:33], v[32:33], v[54:55], v[44:45] op_sel:[1,0,0]
	v_pk_fma_f32 v[30:31], v[2:3], v[30:31], v[48:49]
	v_fmac_f32_e32 v37, v17, v43
	v_pk_fma_f32 v[32:33], v[30:31], v[34:35], v[32:33] op_sel_hi:[0,1,1]
	v_mov_b32_e32 v40, v30
	v_mov_b32_e32 v41, v31
	v_mul_f32_e32 v42, v30, v35
	v_mul_f32_e32 v43, v31, v51
	v_pk_fma_f32 v[30:31], v[30:31], v[50:51], v[32:33] op_sel:[1,0,0]
	v_fmac_f32_e32 v37, v18, v42
	v_fmac_f32_e32 v37, v19, v43
	v_mov_b32_dpp v32, v30 quad_perm:[1,0,3,2] row_mask:0xf bank_mask:0xf bound_ctrl:1
	v_mov_b32_dpp v33, v31 quad_perm:[1,0,3,2] row_mask:0xf bank_mask:0xf bound_ctrl:1
	v_pk_add_f32 v[30:31], v[30:31], v[32:33]
	s_and_b32 s62, s10, 3
	s_movk_i32 s4, 0xff40
	v_mov_b32_dpp v32, v30 quad_perm:[2,3,0,1] row_mask:0xf bank_mask:0xf bound_ctrl:1
	v_mov_b32_dpp v33, v31 quad_perm:[2,3,0,1] row_mask:0xf bank_mask:0xf bound_ctrl:1
	v_pk_add_f32 v[30:31], v[30:31], v[32:33]
	v_mul_lo_u32 v115, v24, s4
	ds_write_b128 v72, v[38:41] offset:16384
	v_mov_b32_dpp v32, v30 row_half_mirror row_mask:0xf bank_mask:0xf bound_ctrl:1
	v_mov_b32_dpp v33, v31 row_half_mirror row_mask:0xf bank_mask:0xf bound_ctrl:1
	v_pk_add_f32 v[34:35], v[30:31], v[32:33]
	v_add_f32_dpp v32, v37, v37 quad_perm:[1,0,3,2] row_mask:0xf bank_mask:0xf bound_ctrl:1
	s_nop 0
	v_mov_b32_dpp v30, v34 row_mirror row_mask:0xf bank_mask:0xf bound_ctrl:1
	v_add_f32_dpp v32, v32, v32 quad_perm:[2,3,0,1] row_mask:0xf bank_mask:0xf bound_ctrl:1
	v_mov_b32_dpp v31, v35 row_mirror row_mask:0xf bank_mask:0xf bound_ctrl:1
	s_nop 0
	v_add_f32_dpp v33, v32, v32 row_half_mirror row_mask:0xf bank_mask:0xf bound_ctrl:1
	v_lshrrev_b32_e32 v32, 2, v36
	v_cmp_eq_u32_e64 s[92:93], s62, v32
	v_and_b32_e32 v32, 12, v113
	v_mov_b32_dpp v37, v33 row_mirror row_mask:0xf bank_mask:0xf bound_ctrl:1
	v_lshlrev_b32_e32 v116, 2, v32
	s_and_saveexec_b64 s[10:11], s[92:93]
	s_cbranch_execz .LBB0_153
	v_lshlrev_b32_e32 v38, 16, v82
	v_and_b32_e32 v39, 0xffff0000, v82
	v_lshlrev_b32_e32 v40, 16, v83
	v_and_b32_e32 v41, 0xffff0000, v83
	v_pk_add_f32 v[28:29], v[28:29], v[40:41] neg_lo:[0,1] neg_hi:[0,1]
	v_pk_add_f32 v[26:27], v[26:27], v[38:39] neg_lo:[0,1] neg_hi:[0,1]
	v_add3_u32 v32, v114, v115, v116
	v_pk_fma_f32 v[26:27], v[4:5], v[26:27], v[38:39]
	v_pk_fma_f32 v[28:29], v[6:7], v[28:29], v[40:41]
	ds_write_b128 v32, v[26:29] offset:20480

; __device__ __forceinline__ u16 f2bf(float f) { return (u16)(pack2(f, 0.f) & 0xffffu); }
; __device__ __forceinline__ void rwkv_scan_job(const P& p, int job, char* smc) {
;     ...
;     if (more) stage(bufs[(c + 1) & 1]);
;     __syncthreads();
;     {
;       const int tt = tid >> 4, ii = tid & 15;
;       const size_t t = (size_t)b * SEQL + c * RW_TC + tt;
;       p.A[t * 1024 + h * 64 + rq * 16 + ii] = f2bf(yb[tt * 16 + ii]);
;     }
.LBB0_161:
	v_lshl_add_u32 v37, v112, 2, s61
	s_waitcnt lgkmcnt(0)
	s_barrier
	ds_read_b32 v37, v37 offset:43264
	s_add_u32 s8, s8, 16
	s_mov_b64 s[6:7], 0x8000
	s_addc_u32 s9, s9, 0
	s_waitcnt lgkmcnt(0)
	v_cvt_pk_bf16_f32 v24, v37, s0
	s_nop 0
	global_store_short v[94:95], v24, off
	v_lshl_add_u64 v[94:95], v[94:95], 0, s[6:7]
	v_lshl_add_u64 v[100:101], v[100:101], 0, s[64:65]
	v_lshl_add_u64 v[102:103], v[102:103], 0, s[66:67]
	s_cmpk_eq_i32 s8, 0x1000
	s_mov_b32 s4, s62
	s_cbranch_scc1 .LBB0_172

; __device__ __forceinline__ void rwkv_scan_job(const P& p, int job, char* smc) {
;     ...
;     RW_LD(0, 0);
;     RW_LD(1, 1);
; #pragma unroll
;     for (int t = 0; t < RW_TC; t++) {
;       if (t + 2 < RW_TC) RW_LD((t + 2) % 3, t + 2);
;       const float4 dec = o_dec[t % 3], kk = o_kk[t % 3], kka = o_kka[t % 3], kp = o_kp[t % 3], wr = o_wr[t % 3];
;       const float vi = o_vi[t % 3], c1 = o_c[t % 3].x, c2 = o_c[t % 3].y;
;       const v2f kk0 = {kk.x, kk.y}, kk1 = {kk.z, kk.w}, wr0 = {wr.x, wr.y}, wr1 = {wr.z, wr.w};
;       v2f ps = Sa * kk0 + Sb * kk1;
;       v2f py = Sa * wr0 + Sb * wr1;
;       float sa = ps.x + ps.y, yd = py.x + py.y;
;       sa = sum16(sa);
;       yv[t] = yd + m0 * (vi * c2 - sa * c1);
;       const v2f dec0 = {dec.x, dec.y}, dec1 = {dec.z, dec.w}, ka0 = {kka.x, kka.y}, ka1 = {kka.z, kka.w},
;                 kp0 = {kp.x, kp.y}, kp1 = {kp.z, kp.w};
;       const v2f sav = {sa, sa}, viv = {vi, vi};
;       Sa = Sa * dec0 - sav * ka0 + viv * kp0;
;       Sb = Sb * dec1 - sav * ka1 + viv * kp1;
;     }
.LBB0_164:
	s_add_i32 s62, s4, 1
	s_and_b32 s4, s4, 1
	s_mul_i32 vcc_lo, s4, 0x5480
	v_lshl_add_u32 v126, v113, 2, vcc_lo
	v_add_u32_e32 v48, vcc_lo, v97
	v_add_u32_e32 v128, 0x5000, v48
	s_lshl_b32 s61, s4, 10
	ds_read_b128 v[144:147], v126 offset:0
	ds_read_b128 v[148:151], v126 offset:4096
	ds_read_b128 v[152:155], v126 offset:8192
	ds_read_b128 v[156:159], v126 offset:12288
	ds_read_b128 v[160:163], v126 offset:16384
	ds_read2_b32 v[184:185], v128 offset0:0 offset1:16
	ds_read_b128 v[164:167], v126 offset:256
	ds_read_b128 v[168:171], v126 offset:4352
	ds_read_b128 v[172:175], v126 offset:8448
	ds_read_b128 v[176:179], v126 offset:12544
	ds_read_b128 v[180:183], v126 offset:16640
	s_waitcnt lgkmcnt(5)
	v_pk_mul_f32 v[52:53], v[32:33], v[148:149]
	v_pk_mul_f32 v[60:61], v[156:157], v[184:185] op_sel_hi:[1,0]
	v_pk_fma_f32 v[52:53], v[34:35], v[150:151], v[52:53]
	ds_read_b128 v[232:235], v126 offset:512
	v_add_f32_e32 v56, v52, v53
	v_pk_mul_f32 v[62:63], v[158:159], v[184:185] op_sel_hi:[1,0]
	ds_read_b128 v[236:239], v126 offset:4608
	v_add_f32_dpp v56, v56, v56 quad_perm:[1,0,3,2] row_mask:0xf bank_mask:0xf bound_ctrl:1
	ds_read_b128 v[240:243], v126 offset:8704
	ds_read_b128 v[244:247], v126 offset:12800
	v_add_f32_dpp v56, v56, v56 quad_perm:[2,3,0,1] row_mask:0xf bank_mask:0xf bound_ctrl:1
	ds_read_b128 v[248:251], v126 offset:16896
	ds_read2_b32 v[186:187], v128 offset0:32 offset1:48
	v_add_f32_dpp v56, v56, v56 row_half_mirror row_mask:0xf bank_mask:0xf bound_ctrl:1
	s_nop 0
	s_nop 0
	v_add_f32_dpp v56, v56, v56 row_mirror row_mask:0xf bank_mask:0xf bound_ctrl:1
	v_pk_fma_f32 v[60:61], v[152:153], v[56:57], v[60:61] op_sel_hi:[1,0,1] neg_lo:[1,0,0] neg_hi:[1,0,0]
	v_pk_fma_f32 v[62:63], v[154:155], v[56:57], v[62:63] op_sel_hi:[1,0,1] neg_lo:[1,0,0] neg_hi:[1,0,0]
	v_pk_fma_f32 v[32:33], v[32:33], v[144:145], v[60:61]
	v_pk_fma_f32 v[34:35], v[34:35], v[146:147], v[62:63]
	s_waitcnt lgkmcnt(6)
	v_pk_mul_f32 v[54:55], v[32:33], v[168:169]
	v_pk_mul_f32 v[68:69], v[34:35], v[162:163]
	v_pk_fma_f32 v[54:55], v[34:35], v[170:171], v[54:55]
	ds_read_b128 v[144:147], v126 offset:768
	v_add_f32_e32 v58, v54, v55
	v_pk_fma_f32 v[68:69], v[32:33], v[160:161], v[68:69]
	ds_read_b128 v[148:151], v126 offset:4864
	v_add_f32_dpp v58, v58, v58 quad_perm:[1,0,3,2] row_mask:0xf bank_mask:0xf bound_ctrl:1
	v_add_f32_e32 v36, v68, v69
	ds_read_b128 v[152:155], v126 offset:8960
	v_add_f32_dpp v58, v58, v58 quad_perm:[2,3,0,1] row_mask:0xf bank_mask:0xf bound_ctrl:1
	v_pk_mul_f32 v[64:65], v[176:177], v[184:185] op_sel:[0,1] op_sel_hi:[1,1]
	ds_read_b128 v[156:159], v126 offset:13056
	v_add_f32_dpp v58, v58, v58 row_half_mirror row_mask:0xf bank_mask:0xf bound_ctrl:1
	v_pk_mul_f32 v[66:67], v[178:179], v[184:185] op_sel:[0,1] op_sel_hi:[1,1]
	ds_read_b128 v[160:163], v126 offset:17152
	v_add_f32_dpp v58, v58, v58 row_mirror row_mask:0xf bank_mask:0xf bound_ctrl:1
	v_pk_fma_f32 v[64:65], v[172:173], v[58:59], v[64:65] op_sel_hi:[1,0,1] neg_lo:[1,0,0] neg_hi:[1,0,0]
	v_pk_fma_f32 v[66:67], v[174:175], v[58:59], v[66:67] op_sel_hi:[1,0,1] neg_lo:[1,0,0] neg_hi:[1,0,0]
	v_pk_fma_f32 v[32:33], v[32:33], v[164:165], v[64:65]
	v_pk_fma_f32 v[34:35], v[34:35], v[166:167], v[66:67]
	s_waitcnt lgkmcnt(5)
	v_pk_mul_f32 v[52:53], v[32:33], v[236:237]
	v_pk_mul_f32 v[70:71], v[34:35], v[182:183]
	v_pk_fma_f32 v[52:53], v[34:35], v[238:239], v[52:53]
	ds_read_b128 v[164:167], v126 offset:1024
	v_add_f32_e32 v56, v52, v53
	v_pk_fma_f32 v[70:71], v[32:33], v[180:181], v[70:71]
	ds_read_b128 v[168:171], v126 offset:5120
	v_add_f32_dpp v56, v56, v56 quad_perm:[1,0,3,2] row_mask:0xf bank_mask:0xf bound_ctrl:1
	v_add_f32_e32 v37, v70, v71
	ds_read_b128 v[172:175], v126 offset:9216
	v_add_f32_dpp v56, v56, v56 quad_perm:[2,3,0,1] row_mask:0xf bank_mask:0xf bound_ctrl:1
	v_pk_mul_f32 v[60:61], v[244:245], v[186:187] op_sel_hi:[1,0]
	ds_read_b128 v[176:179], v126 offset:13312
	v_add_f32_dpp v56, v56, v56 row_half_mirror row_mask:0xf bank_mask:0xf bound_ctrl:1
	v_pk_mul_f32 v[62:63], v[246:247], v[186:187] op_sel_hi:[1,0]
	ds_read_b128 v[180:183], v126 offset:17408
	v_add_f32_dpp v56, v56, v56 row_mirror row_mask:0xf bank_mask:0xf bound_ctrl:1
	ds_read2_b32 v[188:189], v128 offset0:64 offset1:80
	v_pk_fma_f32 v[60:61], v[240:241], v[56:57], v[60:61] op_sel_hi:[1,0,1] neg_lo:[1,0,0] neg_hi:[1,0,0]
	v_pk_fma_f32 v[62:63], v[242:243], v[56:57], v[62:63] op_sel_hi:[1,0,1] neg_lo:[1,0,0] neg_hi:[1,0,0]
	v_pk_fma_f32 v[32:33], v[32:33], v[232:233], v[60:61]
	v_pk_fma_f32 v[34:35], v[34:35], v[234:235], v[62:63]
	s_waitcnt lgkmcnt(6)
	v_pk_mul_f32 v[54:55], v[32:33], v[148:149]
	v_pk_mul_f32 v[68:69], v[34:35], v[250:251]
	v_pk_fma_f32 v[54:55], v[34:35], v[150:151], v[54:55]
	ds_read_b128 v[232:235], v126 offset:1280
	v_add_f32_e32 v58, v54, v55
	v_pk_fma_f32 v[68:69], v[32:33], v[248:249], v[68:69]
	ds_read_b128 v[236:239], v126 offset:5376
	v_add_f32_dpp v58, v58, v58 quad_perm:[1,0,3,2] row_mask:0xf bank_mask:0xf bound_ctrl:1
	v_add_f32_e32 v38, v68, v69
	ds_read_b128 v[240:243], v126 offset:9472
	v_add_f32_dpp v58, v58, v58 quad_perm:[2,3,0,1] row_mask:0xf bank_mask:0xf bound_ctrl:1
	v_pk_mul_f32 v[64:65], v[156:157], v[186:187] op_sel:[0,1] op_sel_hi:[1,1]
	ds_read_b128 v[244:247], v126 offset:13568
	v_add_f32_dpp v58, v58, v58 row_half_mirror row_mask:0xf bank_mask:0xf bound_ctrl:1
	v_pk_mul_f32 v[66:67], v[158:159], v[186:187] op_sel:[0,1] op_sel_hi:[1,1]
	ds_read_b128 v[248:251], v126 offset:17664
	v_add_f32_dpp v58, v58, v58 row_mirror row_mask:0xf bank_mask:0xf bound_ctrl:1
	v_pk_fma_f32 v[64:65], v[152:153], v[58:59], v[64:65] op_sel_hi:[1,0,1] neg_lo:[1,0,0] neg_hi:[1,0,0]
	v_pk_fma_f32 v[66:67], v[154:155], v[58:59], v[66:67] op_sel_hi:[1,0,1] neg_lo:[1,0,0] neg_hi:[1,0,0]
	v_pk_fma_f32 v[32:33], v[32:33], v[144:145], v[64:65]
	v_pk_fma_f32 v[34:35], v[34:35], v[146:147], v[66:67]
	s_waitcnt lgkmcnt(5)
; __device__ __forceinline__ void rwkv_scan_job(const P& p, int job, char* smc) {
;     ...
;     for (int t = 0; t < RW_TC; t++) {
;       if (t + 2 < RW_TC) RW_LD((t + 2) % 3, t + 2);
;       const float4 dec = o_dec[t % 3], kk = o_kk[t % 3], kka = o_kka[t % 3], kp = o_kp[t % 3], wr = o_wr[t % 3];
;       const float vi = o_vi[t % 3], c1 = o_c[t % 3].x, c2 = o_c[t % 3].y;
;       const v2f kk0 = {kk.x, kk.y}, kk1 = {kk.z, kk.w}, wr0 = {wr.x, wr.y}, wr1 = {wr.z, wr.w};
;       v2f ps = Sa * kk0 + Sb * kk1;
;       v2f py = Sa * wr0 + Sb * wr1;
;       float sa = ps.x + ps.y, yd = py.x + py.y;
;       sa = sum16(sa);
;       yv[t] = yd + m0 * (vi * c2 - sa * c1);
;       const v2f dec0 = {dec.x, dec.y}, dec1 = {dec.z, dec.w}, ka0 = {kka.x, kka.y}, ka1 = {kka.z, kka.w},
;                 kp0 = {kp.x, kp.y}, kp1 = {kp.z, kp.w};
;       const v2f sav = {sa, sa}, viv = {vi, vi};
;       Sa = Sa * dec0 - sav * ka0 + viv * kp0;
;       Sb = Sb * dec1 - sav * ka1 + viv * kp1;
;     }
	v_pk_mul_f32 v[52:53], v[32:33], v[168:169]
	v_pk_mul_f32 v[70:71], v[34:35], v[162:163]
	v_pk_fma_f32 v[52:53], v[34:35], v[170:171], v[52:53]
	ds_read_b128 v[144:147], v126 offset:1536
	v_add_f32_e32 v56, v52, v53
	v_pk_fma_f32 v[70:71], v[32:33], v[160:161], v[70:71]
	ds_read_b128 v[148:151], v126 offset:5632
	v_add_f32_dpp v56, v56, v56 quad_perm:[1,0,3,2] row_mask:0xf bank_mask:0xf bound_ctrl:1
	v_add_f32_e32 v39, v70, v71
	ds_read_b128 v[152:155], v126 offset:9728
	v_add_f32_dpp v56, v56, v56 quad_perm:[2,3,0,1] row_mask:0xf bank_mask:0xf bound_ctrl:1
	v_pk_mul_f32 v[60:61], v[176:177], v[188:189] op_sel_hi:[1,0]
	ds_read_b128 v[156:159], v126 offset:13824
	v_add_f32_dpp v56, v56, v56 row_half_mirror row_mask:0xf bank_mask:0xf bound_ctrl:1
	v_pk_mul_f32 v[62:63], v[178:179], v[188:189] op_sel_hi:[1,0]
	ds_read_b128 v[160:163], v126 offset:17920
	v_add_f32_dpp v56, v56, v56 row_mirror row_mask:0xf bank_mask:0xf bound_ctrl:1
	ds_read2_b32 v[184:185], v128 offset0:96 offset1:112
	v_pk_fma_f32 v[60:61], v[172:173], v[56:57], v[60:61] op_sel_hi:[1,0,1] neg_lo:[1,0,0] neg_hi:[1,0,0]
	v_pk_fma_f32 v[62:63], v[174:175], v[56:57], v[62:63] op_sel_hi:[1,0,1] neg_lo:[1,0,0] neg_hi:[1,0,0]
	v_pk_fma_f32 v[32:33], v[32:33], v[164:165], v[60:61]
	v_pk_fma_f32 v[34:35], v[34:35], v[166:167], v[62:63]
	s_waitcnt lgkmcnt(6)
	v_pk_mul_f32 v[54:55], v[32:33], v[236:237]
	v_pk_mul_f32 v[68:69], v[34:35], v[182:183]
	v_pk_fma_f32 v[54:55], v[34:35], v[238:239], v[54:55]
	ds_read_b128 v[164:167], v126 offset:1792
	v_add_f32_e32 v58, v54, v55
	v_pk_fma_f32 v[68:69], v[32:33], v[180:181], v[68:69]
	ds_read_b128 v[168:171], v126 offset:5888
	v_add_f32_dpp v58, v58, v58 quad_perm:[1,0,3,2] row_mask:0xf bank_mask:0xf bound_ctrl:1
	v_add_f32_e32 v40, v68, v69
	ds_read_b128 v[172:175], v126 offset:9984
	v_add_f32_dpp v58, v58, v58 quad_perm:[2,3,0,1] row_mask:0xf bank_mask:0xf bound_ctrl:1
	v_pk_mul_f32 v[64:65], v[244:245], v[188:189] op_sel:[0,1] op_sel_hi:[1,1]
	ds_read_b128 v[176:179], v126 offset:14080
	v_add_f32_dpp v58, v58, v58 row_half_mirror row_mask:0xf bank_mask:0xf bound_ctrl:1
	v_pk_mul_f32 v[66:67], v[246:247], v[188:189] op_sel:[0,1] op_sel_hi:[1,1]
	ds_read_b128 v[180:183], v126 offset:18176
	v_add_f32_dpp v58, v58, v58 row_mirror row_mask:0xf bank_mask:0xf bound_ctrl:1
	v_pk_fma_f32 v[64:65], v[240:241], v[58:59], v[64:65] op_sel_hi:[1,0,1] neg_lo:[1,0,0] neg_hi:[1,0,0]
	v_pk_fma_f32 v[66:67], v[242:243], v[58:59], v[66:67] op_sel_hi:[1,0,1] neg_lo:[1,0,0] neg_hi:[1,0,0]
	v_pk_fma_f32 v[32:33], v[32:33], v[232:233], v[64:65]
	v_pk_fma_f32 v[34:35], v[34:35], v[234:235], v[66:67]
	s_waitcnt lgkmcnt(5)
	v_pk_mul_f32 v[52:53], v[32:33], v[148:149]
	v_pk_mul_f32 v[70:71], v[34:35], v[250:251]
	v_pk_fma_f32 v[52:53], v[34:35], v[150:151], v[52:53]
	ds_read_b128 v[232:235], v126 offset:2048
	v_add_f32_e32 v56, v52, v53
	v_pk_fma_f32 v[70:71], v[32:33], v[248:249], v[70:71]
	ds_read_b128 v[236:239], v126 offset:6144
	v_add_f32_dpp v56, v56, v56 quad_perm:[1,0,3,2] row_mask:0xf bank_mask:0xf bound_ctrl:1
	v_add_f32_e32 v41, v70, v71
	ds_read_b128 v[240:243], v126 offset:10240
	v_add_f32_dpp v56, v56, v56 quad_perm:[2,3,0,1] row_mask:0xf bank_mask:0xf bound_ctrl:1
	v_pk_mul_f32 v[60:61], v[156:157], v[184:185] op_sel_hi:[1,0]
	ds_read_b128 v[244:247], v126 offset:14336
	v_add_f32_dpp v56, v56, v56 row_half_mirror row_mask:0xf bank_mask:0xf bound_ctrl:1
	v_pk_mul_f32 v[62:63], v[158:159], v[184:185] op_sel_hi:[1,0]
	ds_read_b128 v[248:251], v126 offset:18432
	v_add_f32_dpp v56, v56, v56 row_mirror row_mask:0xf bank_mask:0xf bound_ctrl:1
	ds_read2_b32 v[186:187], v128 offset0:128 offset1:144
	v_pk_fma_f32 v[60:61], v[152:153], v[56:57], v[60:61] op_sel_hi:[1,0,1] neg_lo:[1,0,0] neg_hi:[1,0,0]
	v_pk_fma_f32 v[62:63], v[154:155], v[56:57], v[62:63] op_sel_hi:[1,0,1] neg_lo:[1,0,0] neg_hi:[1,0,0]
	v_pk_fma_f32 v[32:33], v[32:33], v[144:145], v[60:61]
	v_pk_fma_f32 v[34:35], v[34:35], v[146:147], v[62:63]
	s_waitcnt lgkmcnt(6)
	v_pk_mul_f32 v[54:55], v[32:33], v[168:169]
	v_pk_mul_f32 v[68:69], v[34:35], v[162:163]
	v_pk_fma_f32 v[54:55], v[34:35], v[170:171], v[54:55]
	ds_read_b128 v[144:147], v126 offset:2304
	v_add_f32_e32 v58, v54, v55
	v_pk_fma_f32 v[68:69], v[32:33], v[160:161], v[68:69]
	ds_read_b128 v[148:151], v126 offset:6400
	v_add_f32_dpp v58, v58, v58 quad_perm:[1,0,3,2] row_mask:0xf bank_mask:0xf bound_ctrl:1
	v_add_f32_e32 v42, v68, v69
	ds_read_b128 v[152:155], v126 offset:10496
	v_add_f32_dpp v58, v58, v58 quad_perm:[2,3,0,1] row_mask:0xf bank_mask:0xf bound_ctrl:1
	v_pk_mul_f32 v[64:65], v[176:177], v[184:185] op_sel:[0,1] op_sel_hi:[1,1]
	ds_read_b128 v[156:159], v126 offset:14592
	v_add_f32_dpp v58, v58, v58 row_half_mirror row_mask:0xf bank_mask:0xf bound_ctrl:1
	v_pk_mul_f32 v[66:67], v[178:179], v[184:185] op_sel:[0,1] op_sel_hi:[1,1]
	ds_read_b128 v[160:163], v126 offset:18688
	v_add_f32_dpp v58, v58, v58 row_mirror row_mask:0xf bank_mask:0xf bound_ctrl:1
	v_pk_fma_f32 v[64:65], v[172:173], v[58:59], v[64:65] op_sel_hi:[1,0,1] neg_lo:[1,0,0] neg_hi:[1,0,0]
	v_pk_fma_f32 v[66:67], v[174:175], v[58:59], v[66:67] op_sel_hi:[1,0,1] neg_lo:[1,0,0] neg_hi:[1,0,0]
	v_pk_fma_f32 v[32:33], v[32:33], v[164:165], v[64:65]
	v_pk_fma_f32 v[34:35], v[34:35], v[166:167], v[66:67]
	s_waitcnt lgkmcnt(5)
; __device__ __forceinline__ void rwkv_scan_job(const P& p, int job, char* smc) {
;     ...
;     for (int t = 0; t < RW_TC; t++) {
;       if (t + 2 < RW_TC) RW_LD((t + 2) % 3, t + 2);
;       const float4 dec = o_dec[t % 3], kk = o_kk[t % 3], kka = o_kka[t % 3], kp = o_kp[t % 3], wr = o_wr[t % 3];
;       const float vi = o_vi[t % 3], c1 = o_c[t % 3].x, c2 = o_c[t % 3].y;
;       const v2f kk0 = {kk.x, kk.y}, kk1 = {kk.z, kk.w}, wr0 = {wr.x, wr.y}, wr1 = {wr.z, wr.w};
;       v2f ps = Sa * kk0 + Sb * kk1;
;       v2f py = Sa * wr0 + Sb * wr1;
;       float sa = ps.x + ps.y, yd = py.x + py.y;
;       sa = sum16(sa);
;       yv[t] = yd + m0 * (vi * c2 - sa * c1);
;       const v2f dec0 = {dec.x, dec.y}, dec1 = {dec.z, dec.w}, ka0 = {kka.x, kka.y}, ka1 = {kka.z, kka.w},
;                 kp0 = {kp.x, kp.y}, kp1 = {kp.z, kp.w};
;       const v2f sav = {sa, sa}, viv = {vi, vi};
;       Sa = Sa * dec0 - sav * ka0 + viv * kp0;
;       Sb = Sb * dec1 - sav * ka1 + viv * kp1;
;     }
	v_pk_mul_f32 v[52:53], v[32:33], v[236:237]
	v_pk_mul_f32 v[70:71], v[34:35], v[182:183]
	v_pk_fma_f32 v[52:53], v[34:35], v[238:239], v[52:53]
	ds_read_b128 v[164:167], v126 offset:2560
	v_add_f32_e32 v56, v52, v53
	v_pk_fma_f32 v[70:71], v[32:33], v[180:181], v[70:71]
	ds_read_b128 v[168:171], v126 offset:6656
	v_add_f32_dpp v56, v56, v56 quad_perm:[1,0,3,2] row_mask:0xf bank_mask:0xf bound_ctrl:1
	v_add_f32_e32 v43, v70, v71
	ds_read_b128 v[172:175], v126 offset:10752
	v_add_f32_dpp v56, v56, v56 quad_perm:[2,3,0,1] row_mask:0xf bank_mask:0xf bound_ctrl:1
	v_pk_mul_f32 v[60:61], v[244:245], v[186:187] op_sel_hi:[1,0]
	ds_read_b128 v[176:179], v126 offset:14848
	v_add_f32_dpp v56, v56, v56 row_half_mirror row_mask:0xf bank_mask:0xf bound_ctrl:1
	v_pk_mul_f32 v[62:63], v[246:247], v[186:187] op_sel_hi:[1,0]
	ds_read_b128 v[180:183], v126 offset:18944
	v_add_f32_dpp v56, v56, v56 row_mirror row_mask:0xf bank_mask:0xf bound_ctrl:1
	ds_read2_b32 v[188:189], v128 offset0:160 offset1:176
	v_pk_fma_f32 v[60:61], v[240:241], v[56:57], v[60:61] op_sel_hi:[1,0,1] neg_lo:[1,0,0] neg_hi:[1,0,0]
	v_pk_fma_f32 v[62:63], v[242:243], v[56:57], v[62:63] op_sel_hi:[1,0,1] neg_lo:[1,0,0] neg_hi:[1,0,0]
	v_pk_fma_f32 v[32:33], v[32:33], v[232:233], v[60:61]
	v_pk_fma_f32 v[34:35], v[34:35], v[234:235], v[62:63]
	s_waitcnt lgkmcnt(6)
	v_pk_mul_f32 v[54:55], v[32:33], v[148:149]
	v_pk_mul_f32 v[68:69], v[34:35], v[250:251]
	v_pk_fma_f32 v[54:55], v[34:35], v[150:151], v[54:55]
	ds_read_b128 v[232:235], v126 offset:2816
	v_add_f32_e32 v58, v54, v55
	v_pk_fma_f32 v[68:69], v[32:33], v[248:249], v[68:69]
	ds_read_b128 v[236:239], v126 offset:6912
	v_add_f32_dpp v58, v58, v58 quad_perm:[1,0,3,2] row_mask:0xf bank_mask:0xf bound_ctrl:1
	v_add_f32_e32 v44, v68, v69
	ds_read_b128 v[240:243], v126 offset:11008
	v_add_f32_dpp v58, v58, v58 quad_perm:[2,3,0,1] row_mask:0xf bank_mask:0xf bound_ctrl:1
	v_pk_mul_f32 v[64:65], v[156:157], v[186:187] op_sel:[0,1] op_sel_hi:[1,1]
	ds_read_b128 v[244:247], v126 offset:15104
	v_add_f32_dpp v58, v58, v58 row_half_mirror row_mask:0xf bank_mask:0xf bound_ctrl:1
	v_pk_mul_f32 v[66:67], v[158:159], v[186:187] op_sel:[0,1] op_sel_hi:[1,1]
	ds_read_b128 v[248:251], v126 offset:19200
	v_add_f32_dpp v58, v58, v58 row_mirror row_mask:0xf bank_mask:0xf bound_ctrl:1
	v_pk_fma_f32 v[64:65], v[152:153], v[58:59], v[64:65] op_sel_hi:[1,0,1] neg_lo:[1,0,0] neg_hi:[1,0,0]
	v_pk_fma_f32 v[66:67], v[154:155], v[58:59], v[66:67] op_sel_hi:[1,0,1] neg_lo:[1,0,0] neg_hi:[1,0,0]
	v_pk_fma_f32 v[32:33], v[32:33], v[144:145], v[64:65]
	v_pk_fma_f32 v[34:35], v[34:35], v[146:147], v[66:67]
	s_waitcnt lgkmcnt(5)
	v_pk_mul_f32 v[52:53], v[32:33], v[168:169]
	v_pk_mul_f32 v[70:71], v[34:35], v[162:163]
	v_pk_fma_f32 v[52:53], v[34:35], v[170:171], v[52:53]
	ds_read_b128 v[144:147], v126 offset:3072
	v_add_f32_e32 v56, v52, v53
	v_pk_fma_f32 v[70:71], v[32:33], v[160:161], v[70:71]
	ds_read_b128 v[148:151], v126 offset:7168
	v_add_f32_dpp v56, v56, v56 quad_perm:[1,0,3,2] row_mask:0xf bank_mask:0xf bound_ctrl:1
	v_add_f32_e32 v45, v70, v71
	ds_read_b128 v[152:155], v126 offset:11264
	v_add_f32_dpp v56, v56, v56 quad_perm:[2,3,0,1] row_mask:0xf bank_mask:0xf bound_ctrl:1
	v_pk_mul_f32 v[60:61], v[176:177], v[188:189] op_sel_hi:[1,0]
	ds_read_b128 v[156:159], v126 offset:15360
	v_add_f32_dpp v56, v56, v56 row_half_mirror row_mask:0xf bank_mask:0xf bound_ctrl:1
	v_pk_mul_f32 v[62:63], v[178:179], v[188:189] op_sel_hi:[1,0]
	ds_read_b128 v[160:163], v126 offset:19456
	v_add_f32_dpp v56, v56, v56 row_mirror row_mask:0xf bank_mask:0xf bound_ctrl:1
	ds_read2_b32 v[184:185], v128 offset0:192 offset1:208
	v_pk_fma_f32 v[60:61], v[172:173], v[56:57], v[60:61] op_sel_hi:[1,0,1] neg_lo:[1,0,0] neg_hi:[1,0,0]
	v_pk_fma_f32 v[62:63], v[174:175], v[56:57], v[62:63] op_sel_hi:[1,0,1] neg_lo:[1,0,0] neg_hi:[1,0,0]
	v_pk_fma_f32 v[32:33], v[32:33], v[164:165], v[60:61]
	v_pk_fma_f32 v[34:35], v[34:35], v[166:167], v[62:63]
	s_waitcnt lgkmcnt(6)
	v_pk_mul_f32 v[54:55], v[32:33], v[236:237]
	v_pk_mul_f32 v[68:69], v[34:35], v[182:183]
	v_pk_fma_f32 v[54:55], v[34:35], v[238:239], v[54:55]
	ds_read_b128 v[164:167], v126 offset:3328
	v_add_f32_e32 v58, v54, v55
	v_pk_fma_f32 v[68:69], v[32:33], v[180:181], v[68:69]
	ds_read_b128 v[168:171], v126 offset:7424
	v_add_f32_dpp v58, v58, v58 quad_perm:[1,0,3,2] row_mask:0xf bank_mask:0xf bound_ctrl:1
	v_add_f32_e32 v46, v68, v69
	ds_read_b128 v[172:175], v126 offset:11520
	v_add_f32_dpp v58, v58, v58 quad_perm:[2,3,0,1] row_mask:0xf bank_mask:0xf bound_ctrl:1
	v_pk_mul_f32 v[64:65], v[244:245], v[188:189] op_sel:[0,1] op_sel_hi:[1,1]
	ds_read_b128 v[176:179], v126 offset:15616
	v_add_f32_dpp v58, v58, v58 row_half_mirror row_mask:0xf bank_mask:0xf bound_ctrl:1
	v_pk_mul_f32 v[66:67], v[246:247], v[188:189] op_sel:[0,1] op_sel_hi:[1,1]
	ds_read_b128 v[180:183], v126 offset:19712
	v_add_f32_dpp v58, v58, v58 row_mirror row_mask:0xf bank_mask:0xf bound_ctrl:1
	v_pk_fma_f32 v[64:65], v[240:241], v[58:59], v[64:65] op_sel_hi:[1,0,1] neg_lo:[1,0,0] neg_hi:[1,0,0]
	v_pk_fma_f32 v[66:67], v[242:243], v[58:59], v[66:67] op_sel_hi:[1,0,1] neg_lo:[1,0,0] neg_hi:[1,0,0]
	v_pk_fma_f32 v[32:33], v[32:33], v[232:233], v[64:65]
	v_pk_fma_f32 v[34:35], v[34:35], v[234:235], v[66:67]
	s_waitcnt lgkmcnt(5)
; __device__ __forceinline__ void rwkv_scan_job(const P& p, int job, char* smc) {
;     ...
;     for (int t = 0; t < RW_TC; t++) {
;       if (t + 2 < RW_TC) RW_LD((t + 2) % 3, t + 2);
;       const float4 dec = o_dec[t % 3], kk = o_kk[t % 3], kka = o_kka[t % 3], kp = o_kp[t % 3], wr = o_wr[t % 3];
;       const float vi = o_vi[t % 3], c1 = o_c[t % 3].x, c2 = o_c[t % 3].y;
;       const v2f kk0 = {kk.x, kk.y}, kk1 = {kk.z, kk.w}, wr0 = {wr.x, wr.y}, wr1 = {wr.z, wr.w};
;       v2f ps = Sa * kk0 + Sb * kk1;
;       v2f py = Sa * wr0 + Sb * wr1;
;       float sa = ps.x + ps.y, yd = py.x + py.y;
;       sa = sum16(sa);
;       yv[t] = yd + m0 * (vi * c2 - sa * c1);
;       const v2f dec0 = {dec.x, dec.y}, dec1 = {dec.z, dec.w}, ka0 = {kka.x, kka.y}, ka1 = {kka.z, kka.w},
;                 kp0 = {kp.x, kp.y}, kp1 = {kp.z, kp.w};
;       const v2f sav = {sa, sa}, viv = {vi, vi};
;       Sa = Sa * dec0 - sav * ka0 + viv * kp0;
;       Sb = Sb * dec1 - sav * ka1 + viv * kp1;
;     }
;     ...
;     {
;       float r8[8], r4[4], r2[2];
; #pragma unroll
;       for (int i = 0; i < 8; i++) {
;         const float keep = b3 ? yv[i + 8] : yv[i], send = b3 ? yv[i] : yv[i + 8];
;         r8[i] = keep + dppf<0x128>(send);
	v_pk_mul_f32 v[52:53], v[32:33], v[148:149]
	v_pk_mul_f32 v[70:71], v[34:35], v[250:251]
	v_pk_fma_f32 v[52:53], v[34:35], v[150:151], v[52:53]
	ds_read_b128 v[232:235], v126 offset:3584
	v_add_f32_e32 v56, v52, v53
	v_pk_fma_f32 v[70:71], v[32:33], v[248:249], v[70:71]
	ds_read_b128 v[236:239], v126 offset:7680
	v_add_f32_dpp v56, v56, v56 quad_perm:[1,0,3,2] row_mask:0xf bank_mask:0xf bound_ctrl:1
	v_add_f32_e32 v47, v70, v71
	ds_read_b128 v[240:243], v126 offset:11776
	v_add_f32_dpp v56, v56, v56 quad_perm:[2,3,0,1] row_mask:0xf bank_mask:0xf bound_ctrl:1
	v_pk_mul_f32 v[60:61], v[156:157], v[184:185] op_sel_hi:[1,0]
	ds_read_b128 v[244:247], v126 offset:15872
	v_add_f32_dpp v56, v56, v56 row_half_mirror row_mask:0xf bank_mask:0xf bound_ctrl:1
	v_pk_mul_f32 v[62:63], v[158:159], v[184:185] op_sel_hi:[1,0]
	ds_read_b128 v[248:251], v126 offset:19968
	v_add_f32_dpp v56, v56, v56 row_mirror row_mask:0xf bank_mask:0xf bound_ctrl:1
	ds_read2_b32 v[186:187], v128 offset0:224 offset1:240
	v_pk_fma_f32 v[60:61], v[152:153], v[56:57], v[60:61] op_sel_hi:[1,0,1] neg_lo:[1,0,0] neg_hi:[1,0,0]
	v_pk_fma_f32 v[62:63], v[154:155], v[56:57], v[62:63] op_sel_hi:[1,0,1] neg_lo:[1,0,0] neg_hi:[1,0,0]
	v_pk_fma_f32 v[32:33], v[32:33], v[144:145], v[60:61]
	v_pk_fma_f32 v[34:35], v[34:35], v[146:147], v[62:63]
	s_waitcnt lgkmcnt(6)
	v_pk_mul_f32 v[54:55], v[32:33], v[168:169]
	v_pk_mul_f32 v[68:69], v[34:35], v[162:163]
	v_pk_fma_f32 v[54:55], v[34:35], v[170:171], v[54:55]
	ds_read_b128 v[144:147], v126 offset:3840
	v_add_f32_e32 v58, v54, v55
	v_pk_fma_f32 v[68:69], v[32:33], v[160:161], v[68:69]
	ds_read_b128 v[148:151], v126 offset:7936
	v_add_f32_dpp v58, v58, v58 quad_perm:[1,0,3,2] row_mask:0xf bank_mask:0xf bound_ctrl:1
	v_add_f32_e32 v48, v68, v69
	ds_read_b128 v[152:155], v126 offset:12032
	v_add_f32_dpp v58, v58, v58 quad_perm:[2,3,0,1] row_mask:0xf bank_mask:0xf bound_ctrl:1
	v_pk_mul_f32 v[64:65], v[176:177], v[184:185] op_sel:[0,1] op_sel_hi:[1,1]
	ds_read_b128 v[156:159], v126 offset:16128
	v_add_f32_dpp v58, v58, v58 row_half_mirror row_mask:0xf bank_mask:0xf bound_ctrl:1
	v_pk_mul_f32 v[66:67], v[178:179], v[184:185] op_sel:[0,1] op_sel_hi:[1,1]
	ds_read_b128 v[160:163], v126 offset:20224
	v_add_f32_dpp v58, v58, v58 row_mirror row_mask:0xf bank_mask:0xf bound_ctrl:1
	v_pk_fma_f32 v[64:65], v[172:173], v[58:59], v[64:65] op_sel_hi:[1,0,1] neg_lo:[1,0,0] neg_hi:[1,0,0]
	v_pk_fma_f32 v[66:67], v[174:175], v[58:59], v[66:67] op_sel_hi:[1,0,1] neg_lo:[1,0,0] neg_hi:[1,0,0]
	v_pk_fma_f32 v[32:33], v[32:33], v[164:165], v[64:65]
	v_pk_fma_f32 v[34:35], v[34:35], v[166:167], v[66:67]
	s_waitcnt lgkmcnt(5)
	v_pk_mul_f32 v[52:53], v[32:33], v[236:237]
	v_pk_mul_f32 v[70:71], v[34:35], v[182:183]
	v_pk_fma_f32 v[52:53], v[34:35], v[238:239], v[52:53]
	v_pk_mul_f32 v[60:61], v[244:245], v[186:187] op_sel_hi:[1,0]
	v_add_f32_e32 v56, v52, v53
	v_pk_fma_f32 v[70:71], v[32:33], v[180:181], v[70:71]
	v_pk_mul_f32 v[62:63], v[246:247], v[186:187] op_sel_hi:[1,0]
	v_add_f32_dpp v56, v56, v56 quad_perm:[1,0,3,2] row_mask:0xf bank_mask:0xf bound_ctrl:1
	v_add_f32_e32 v49, v70, v71
	s_nop 0
	v_add_f32_dpp v56, v56, v56 quad_perm:[2,3,0,1] row_mask:0xf bank_mask:0xf bound_ctrl:1
	s_nop 0
	s_nop 0
	v_add_f32_dpp v56, v56, v56 row_half_mirror row_mask:0xf bank_mask:0xf bound_ctrl:1
	s_nop 0
	s_nop 0
	v_add_f32_dpp v56, v56, v56 row_mirror row_mask:0xf bank_mask:0xf bound_ctrl:1
	v_pk_fma_f32 v[60:61], v[240:241], v[56:57], v[60:61] op_sel_hi:[1,0,1] neg_lo:[1,0,0] neg_hi:[1,0,0]
	v_pk_fma_f32 v[62:63], v[242:243], v[56:57], v[62:63] op_sel_hi:[1,0,1] neg_lo:[1,0,0] neg_hi:[1,0,0]
	v_pk_fma_f32 v[32:33], v[32:33], v[232:233], v[60:61]
	v_pk_fma_f32 v[34:35], v[34:35], v[234:235], v[62:63]
	s_waitcnt lgkmcnt(0)
	v_pk_mul_f32 v[54:55], v[32:33], v[148:149]
	v_pk_mul_f32 v[68:69], v[34:35], v[250:251]
	v_pk_fma_f32 v[54:55], v[34:35], v[150:151], v[54:55]
	v_pk_mul_f32 v[64:65], v[156:157], v[186:187] op_sel:[0,1] op_sel_hi:[1,1]
	v_add_f32_e32 v58, v54, v55
	v_pk_fma_f32 v[68:69], v[32:33], v[248:249], v[68:69]
	v_pk_mul_f32 v[66:67], v[158:159], v[186:187] op_sel:[0,1] op_sel_hi:[1,1]
	v_add_f32_dpp v58, v58, v58 quad_perm:[1,0,3,2] row_mask:0xf bank_mask:0xf bound_ctrl:1
	v_add_f32_e32 v50, v68, v69
	s_nop 0
	v_add_f32_dpp v58, v58, v58 quad_perm:[2,3,0,1] row_mask:0xf bank_mask:0xf bound_ctrl:1
	s_nop 0
	s_nop 0
	v_add_f32_dpp v58, v58, v58 row_half_mirror row_mask:0xf bank_mask:0xf bound_ctrl:1
	s_nop 0
	s_nop 0
	v_add_f32_dpp v58, v58, v58 row_mirror row_mask:0xf bank_mask:0xf bound_ctrl:1
	v_pk_fma_f32 v[64:65], v[152:153], v[58:59], v[64:65] op_sel_hi:[1,0,1] neg_lo:[1,0,0] neg_hi:[1,0,0]
	v_pk_fma_f32 v[66:67], v[154:155], v[58:59], v[66:67] op_sel_hi:[1,0,1] neg_lo:[1,0,0] neg_hi:[1,0,0]
	v_pk_fma_f32 v[32:33], v[32:33], v[144:145], v[64:65]
	v_pk_fma_f32 v[34:35], v[34:35], v[146:147], v[66:67]
	s_nop 0
	v_pk_mul_f32 v[70:71], v[34:35], v[162:163]
	s_nop 0
	v_pk_fma_f32 v[70:71], v[32:33], v[160:161], v[70:71]
	s_nop 0
	v_add_f32_e32 v51, v70, v71
	v_cndmask_b32_e64 v104, v44, v36, s[10:11]
	v_cndmask_b32_e64 v105, v36, v44, s[10:11]
	v_cndmask_b32_e64 v106, v45, v37, s[10:11]
	v_cndmask_b32_e64 v107, v37, v45, s[10:11]
	v_cndmask_b32_e64 v108, v46, v38, s[10:11]
	v_cndmask_b32_e64 v109, v38, v46, s[10:11]
	v_cndmask_b32_e64 v110, v47, v39, s[10:11]
	v_cndmask_b32_e64 v111, v39, v47, s[10:11]
	v_cndmask_b32_e64 v24, v48, v40, s[10:11]
	v_cndmask_b32_e64 v25, v40, v48, s[10:11]
	v_cndmask_b32_e64 v26, v49, v41, s[10:11]
	v_cndmask_b32_e64 v27, v41, v49, s[10:11]
	v_cndmask_b32_e64 v28, v50, v42, s[10:11]
	v_cndmask_b32_e64 v29, v42, v50, s[10:11]
; __device__ __forceinline__ void unpack4(uint2 u, float* f) { f[0] = bflo(u.x); f[1] = bfhi(u.x); f[2] = bflo(u.y); f[3] = bfhi(u.y); }
; __device__ __forceinline__ void rwkv_scan_job(const P& p, int job, char* smc) {
;     ...
;   auto stage = [&](RwBuf& bf) {
;     float r[4], rp[4], k[4], kpv[4], v[4], vp[4], ld[4], a[4];
;     unpack4(g_r, r); unpack4(g_rp, rp); unpack4(g_k, k); unpack4(g_kp, kpv); unpack4(g_v, v); unpack4(g_vp, vp);
;     if (g_first) {
; #pragma unroll
;       for (int i = 0; i < 4; i++) { rp[i] = 0.f; kpv[i] = 0.f; vp[i] = 0.f; }
;     }
;     unpack4(g_ld, ld); unpack4(g_a, a);
;     ...
;     {
;       float r8[8], r4[4], r2[2];
; #pragma unroll
;       for (int i = 0; i < 8; i++) {
;         const float keep = b3 ? yv[i + 8] : yv[i], send = b3 ? yv[i] : yv[i + 8];
;         r8[i] = keep + dppf<0x128>(send);
;       }
; #pragma unroll
;       for (int i = 0; i < 4; i++) {
;         const float keep = b2 ? r8[i + 4] : r8[i], send = b2 ? r8[i] : r8[i + 4];
;         r4[i] = keep + dppf<0x141>(send);
;       }
; #pragma unroll
;       for (int i = 0; i < 2; i++) {
;         const float keep = b1 ? r4[i + 2] : r4[i], send = b1 ? r4[i] : r4[i + 2];
;         r2[i] = keep + dppf<0x4E>(send);
;       }
;       const float keep = b0 ? r2[1] : r2[0], send = b0 ? r2[0] : r2[1];
;       const float ysum = keep + dppf<0xB1>(send);
;       yb[(lane & 15) * 16 + il] = ysum;
;     }
	v_cndmask_b32_e64 v30, v51, v43, s[10:11]
	v_cndmask_b32_e64 v31, v43, v51, s[10:11]
	v_add_f32_dpp v36, v105, v104 row_ror:8 row_mask:0xf bank_mask:0xf bound_ctrl:1
	v_add_f32_dpp v37, v107, v106 row_ror:8 row_mask:0xf bank_mask:0xf bound_ctrl:1
	v_add_f32_dpp v38, v109, v108 row_ror:8 row_mask:0xf bank_mask:0xf bound_ctrl:1
	v_add_f32_dpp v39, v111, v110 row_ror:8 row_mask:0xf bank_mask:0xf bound_ctrl:1
	v_add_f32_dpp v40, v25, v24 row_ror:8 row_mask:0xf bank_mask:0xf bound_ctrl:1
	v_add_f32_dpp v41, v27, v26 row_ror:8 row_mask:0xf bank_mask:0xf bound_ctrl:1
	v_add_f32_dpp v42, v29, v28 row_ror:8 row_mask:0xf bank_mask:0xf bound_ctrl:1
	v_add_f32_dpp v43, v31, v30 row_ror:8 row_mask:0xf bank_mask:0xf bound_ctrl:1
	v_cndmask_b32_e64 v104, v40, v36, s[12:13]
	v_cndmask_b32_e64 v105, v36, v40, s[12:13]
	v_cndmask_b32_e64 v106, v41, v37, s[12:13]
	v_cndmask_b32_e64 v107, v37, v41, s[12:13]
	v_cndmask_b32_e64 v108, v42, v38, s[12:13]
	v_cndmask_b32_e64 v109, v38, v42, s[12:13]
	v_cndmask_b32_e64 v110, v43, v39, s[12:13]
	v_cndmask_b32_e64 v111, v39, v43, s[12:13]
	v_add_f32_dpp v36, v105, v104 row_half_mirror row_mask:0xf bank_mask:0xf bound_ctrl:1
	v_add_f32_dpp v37, v107, v106 row_half_mirror row_mask:0xf bank_mask:0xf bound_ctrl:1
	v_add_f32_dpp v38, v109, v108 row_half_mirror row_mask:0xf bank_mask:0xf bound_ctrl:1
	v_add_f32_dpp v39, v111, v110 row_half_mirror row_mask:0xf bank_mask:0xf bound_ctrl:1
	v_cndmask_b32_e64 v104, v38, v36, s[14:15]
	v_cndmask_b32_e64 v105, v36, v38, s[14:15]
	v_cndmask_b32_e64 v106, v39, v37, s[14:15]
	v_cndmask_b32_e64 v107, v37, v39, s[14:15]
	s_nop 1
	v_add_f32_dpp v36, v105, v104 quad_perm:[2,3,0,1] row_mask:0xf bank_mask:0xf bound_ctrl:1
	v_add_f32_dpp v37, v107, v106 quad_perm:[2,3,0,1] row_mask:0xf bank_mask:0xf bound_ctrl:1
	v_cndmask_b32_e64 v104, v37, v36, s[16:17]
	v_cndmask_b32_e64 v105, v36, v37, s[16:17]
	s_nop 1
	v_add_f32_dpp v36, v105, v104 quad_perm:[1,0,3,2] row_mask:0xf bank_mask:0xf bound_ctrl:1
	v_or_b32_e32 v24, s61, v119
	v_add_u32_e32 v24, v24, v97
	s_andn2_b64 vcc, exec, s[6:7]
	ds_write_b32 v24, v36 offset:43264
	s_cbranch_vccnz .LBB0_161
	s_waitcnt vmcnt(4)
	v_lshlrev_b32_e32 v42, 16, v80
	v_and_b32_e32 v43, 0xffff0000, v80
	v_lshlrev_b32_e32 v40, 16, v81
	v_and_b32_e32 v41, 0xffff0000, v81
	s_waitcnt vmcnt(3)
	v_lshlrev_b32_e32 v50, 16, v86
	v_and_b32_e32 v51, 0xffff0000, v86
	v_lshlrev_b32_e32 v52, 16, v87
	v_and_b32_e32 v53, 0xffff0000, v87
	s_waitcnt vmcnt(2)
	v_lshlrev_b32_e32 v36, 16, v88
	v_and_b32_e32 v37, 0xffff0000, v88
	v_lshlrev_b32_e32 v38, 16, v89
	v_and_b32_e32 v39, 0xffff0000, v89
	s_and_saveexec_b64 s[6:7], s[94:95]
	s_cbranch_execz .LBB0_167
	v_mov_b32_e32 v50, 0
	v_mov_b32_e32 v51, v50
	v_mov_b32_e32 v52, v50
	v_mov_b32_e32 v53, v50
	v_mov_b32_e32 v42, v50
	v_mov_b32_e32 v43, v50
	v_mov_b32_e32 v40, v50
	v_mov_b32_e32 v41, v50
	v_mov_b32_e32 v36, v50
	v_mov_b32_e32 v37, v50
	v_mov_b32_e32 v38, v50
	v_mov_b32_e32 v39, v50
; __device__ __forceinline__ void unpack4(uint2 u, float* f) { f[0] = bflo(u.x); f[1] = bfhi(u.x); f[2] = bflo(u.y); f[3] = bfhi(u.y); }
; __device__ __forceinline__ void rwkv_scan_job(const P& p, int job, char* smc) {
;     ...
;   auto stage = [&](RwBuf& bf) {
;     float r[4], rp[4], k[4], kpv[4], v[4], vp[4], ld[4], a[4];
;     unpack4(g_r, r); unpack4(g_rp, rp); unpack4(g_k, k); unpack4(g_kp, kpv); unpack4(g_v, v); unpack4(g_vp, vp);
;     if (g_first) {
; #pragma unroll
;       for (int i = 0; i < 4; i++) { rp[i] = 0.f; kpv[i] = 0.f; vp[i] = 0.f; }
;     }
;     unpack4(g_ld, ld); unpack4(g_a, a);
;     float kkr[4], kpr[4], rs[4], vs[4], ss = 0.f;
; #pragma unroll
;     for (int i = 0; i < 4; i++) {
;       rs[i] = r[i] + (rp[i] - r[i]) * mur[i];
;       float ks = k[i] + (kpv[i] - k[i]) * muk[i];
;       vs[i] = v[i] + (vp[i] - v[i]) * muv[i];
;       kkr[i] = ks * kkc[i];
;       ss += kkr[i] * kkr[i];
;       kpr[i] = ks * (1.f + (a[i] - 1.f) * kac[i]);
;     }
;     ss = sum16(ss);
;     const float inv = rsqrtf(fmaxf(ss, 1e-24f));
;     float c1 = 0.f, c2 = 0.f, c3 = 0.f;
;     float dk[4], kk4[4], kka4[4], wr4[4];
; #pragma unroll
;     for (int i = 0; i < 4; i++) {
;       kk4[i] = kkr[i] * inv;
;       kka4[i] = kk4[i] * a[i];
;       dk[i] = __expf(ld[i]);
;       wr4[i] = dk[i] * rs[i];
;       c1 += kka4[i] * rs[i];
;       c2 += kpr[i] * rs[i];
;       c3 += kpr[i] * rs[i] * rkc[i];
;     }
;     c1 = sum16(c1); c2 = sum16(c2); c3 = sum16(c3);
;     *(float4*)&bf.dec[tl][jg * 4] = make_float4(dk[0], dk[1], dk[2], dk[3]);
;     *(float4*)&bf.kk[tl][jg * 4] = make_float4(kk4[0], kk4[1], kk4[2], kk4[3]);
;     *(float4*)&bf.kka[tl][jg * 4] = make_float4(kka4[0], kka4[1], kka4[2], kka4[3]);
;     *(float4*)&bf.kp[tl][jg * 4] = make_float4(kpr[0], kpr[1], kpr[2], kpr[3]);
;     *(float4*)&bf.wr[tl][jg * 4] = make_float4(wr4[0], wr4[1], wr4[2], wr4[3]);
;     if ((jg >> 2) == rq) *(float4*)&bf.v[tl][(jg & 3) * 4] = make_float4(vs[0], vs[1], vs[2], vs[3]);
;     if (jg == 0) { bf.c[tl][0] = c1; bf.c[tl][1] = c2; if (rq == 0) p.c3buf[(size_t)g_t * 8 + h] = c3; }
;   };
.LBB0_167:
	s_or_b64 exec, exec, s[6:7]
	v_lshlrev_b32_e32 v60, 16, v79
	v_lshlrev_b32_e32 v58, 16, v78
	v_and_b32_e32 v59, 0xffff0000, v78
	v_and_b32_e32 v66, 0xffff0000, v79
	s_waitcnt vmcnt(0)
	v_lshlrev_b32_e32 v68, 16, v92
	v_sub_f32_e32 v52, v52, v60
	v_and_b32_e32 v70, 0xffff0000, v92
	v_add_f32_e32 v69, -1.0, v68
	v_mul_f32_e32 v104, v14, v52
	v_sub_f32_e32 v52, v53, v66
	v_pk_add_f32 v[50:51], v[50:51], v[58:59] neg_lo:[0,1] neg_hi:[0,1]
	v_lshlrev_b32_e32 v61, 16, v93
	v_and_b32_e32 v67, 0xffff0000, v93
	v_fma_f32 v73, v8, v69, 1.0
	v_add_f32_e32 v69, -1.0, v70
	v_mul_f32_e32 v138, v15, v52
	v_pk_fma_f32 v[50:51], v[12:13], v[50:51], v[58:59]
	v_mov_b32_e32 v105, v139
	v_fma_f32 v75, v9, v69, 1.0
	v_pk_add_f32 v[106:107], v[138:139], v[66:67]
	v_pk_mul_f32 v[58:59], v[20:21], v[50:51]
	v_mov_b32_e32 v69, v50
	v_mov_b32_e32 v71, v51
	v_pk_add_f32 v[50:51], v[104:105], v[60:61]
	v_pk_mul_f32 v[108:109], v[10:11], v[106:107]
	v_pk_mul_f32 v[104:105], v[22:23], v[50:51]
	v_pk_mul_f32 v[110:111], v[58:59], v[58:59]
	v_mov_b32_e32 v120, v108
	v_mov_b32_e32 v121, v104
	v_pk_mul_f32 v[120:121], v[120:121], v[120:121]
	v_add_f32_e32 v60, v110, v111
	v_add_f32_e32 v60, v121, v60
	v_add_f32_e32 v60, v120, v60
	v_lshlrev_b32_e32 v54, 16, v90
	v_and_b32_e32 v55, 0xffff0000, v90
	v_add_f32_dpp v60, v60, v60 quad_perm:[1,0,3,2] row_mask:0xf bank_mask:0xf bound_ctrl:1
	v_mul_f32_e32 v52, 0x3fb8aa3b, v54
	v_lshlrev_b32_e32 v56, 16, v91
	v_add_f32_dpp v60, v60, v60 quad_perm:[2,3,0,1] row_mask:0xf bank_mask:0xf bound_ctrl:1
	v_exp_f32_e32 v54, v52
	v_mul_f32_e32 v52, 0x3fb8aa3b, v55
	v_add_f32_dpp v60, v60, v60 row_half_mirror row_mask:0xf bank_mask:0xf bound_ctrl:1
	s_and_b32 s4, s62, 1
	v_and_b32_e32 v57, 0xffff0000, v91
	v_add_f32_dpp v60, v60, v60 row_mirror row_mask:0xf bank_mask:0xf bound_ctrl:1
	v_max_f32_e32 v60, 0x179abe15, v60
	v_rsq_f32_e32 v140, v60
	v_exp_f32_e32 v55, v52
	v_mul_f32_e32 v52, 0x3fb8aa3b, v56
	s_mov_b32 s7, 1.0
	v_pk_mul_f32 v[58:59], v[58:59], v[140:141] op_sel_hi:[1,0]
	v_exp_f32_e32 v56, v52
	v_mov_b32_e32 v72, v58
	v_mov_b32_e32 v74, v59
	v_mul_f32_e32 v52, 0x3fb8aa3b, v57
	s_mulk_i32 s4, 0x5480
	v_mov_b32_e32 v122, v61
	v_mov_b32_e32 v123, v50
	v_pk_mul_f32 v[68:69], v[72:73], v[68:69]
	v_pk_mul_f32 v[70:71], v[74:75], v[70:71]
	v_pk_mul_f32 v[60:61], v[104:105], v[140:141]
	v_pk_fma_f32 v[50:51], v[22:23], v[50:51], s[6:7]
	v_pk_mul_f32 v[72:73], v[108:109], v[140:141]
	v_pk_fma_f32 v[74:75], v[10:11], v[106:107], s[6:7]
	v_exp_f32_e32 v57, v52
	v_pk_mov_b32 v[66:67], v[66:67], v[106:107] op_sel:[1,0]
	v_add_u32_e32 v52, s4, v114
	v_mov_b32_e32 v61, v51
	v_mov_b32_e32 v73, v75
	v_lshlrev_b32_e32 v62, 16, v76
	v_and_b32_e32 v63, 0xffff0000, v76
	v_lshl_add_u32 v53, v113, 2, v52
	v_pk_mul_f32 v[50:51], v[60:61], v[122:123]
	v_pk_mul_f32 v[66:67], v[72:73], v[66:67]
	v_mov_b32_e32 v61, v72
	ds_write_b128 v53, v[58:61] offset:4096
	v_mov_b32_e32 v58, v68
	v_mov_b32_e32 v59, v70
	v_mov_b32_e32 v60, v50
	v_mov_b32_e32 v61, v66
	v_pk_add_f32 v[42:43], v[42:43], v[62:63] neg_lo:[0,1] neg_hi:[0,1]
	v_lshlrev_b32_e32 v64, 16, v77
	v_and_b32_e32 v65, 0xffff0000, v77
	ds_write_b128 v53, v[58:61] offset:8192
	v_mov_b32_e32 v58, v69
	v_mov_b32_e32 v59, v71
	v_mov_b32_e32 v60, v51
	v_mov_b32_e32 v61, v67
	v_pk_fma_f32 v[42:43], v[0:1], v[42:43], v[62:63]
	ds_write_b128 v53, v[58:61] offset:12288
	v_pk_mul_f32 v[58:59], v[42:43], v[68:69] op_sel_hi:[0,1]
	v_pk_fma_f32 v[60:61], v[42:43], v[68:69], 0 op_sel_hi:[0,1,0]
	v_pk_add_f32 v[40:41], v[40:41], v[64:65] neg_lo:[0,1] neg_hi:[0,1]
	ds_write_b128 v53, v[54:57]
	v_mov_b32_e32 v54, v42
	v_mov_b32_e32 v55, v43
	v_fma_f32 v62, v16, v59, 0
	v_pk_mul_f32 v[58:59], v[42:43], v[70:71]
	v_pk_fma_f32 v[42:43], v[42:43], v[70:71], v[60:61] op_sel:[1,0,0]
	v_pk_fma_f32 v[40:41], v[2:3], v[40:41], v[64:65]
	v_fmac_f32_e32 v62, v17, v59
	v_pk_fma_f32 v[42:43], v[40:41], v[50:51], v[42:43] op_sel_hi:[0,1,1]
	v_mov_b32_e32 v56, v40
	v_mov_b32_e32 v57, v41
	v_mul_f32_e32 v58, v40, v51
	v_mul_f32_e32 v59, v41, v67
	v_pk_fma_f32 v[40:41], v[40:41], v[66:67], v[42:43] op_sel:[1,0,0]
	v_fmac_f32_e32 v62, v18, v58
	v_fmac_f32_e32 v62, v19, v59
	v_mov_b32_dpp v42, v40 quad_perm:[1,0,3,2] row_mask:0xf bank_mask:0xf bound_ctrl:1
	v_mov_b32_dpp v43, v41 quad_perm:[1,0,3,2] row_mask:0xf bank_mask:0xf bound_ctrl:1
	v_pk_add_f32 v[40:41], v[40:41], v[42:43]
	v_add_f32_dpp v50, v62, v62 quad_perm:[1,0,3,2] row_mask:0xf bank_mask:0xf bound_ctrl:1
	ds_write_b128 v53, v[54:57] offset:16384
	v_mov_b32_dpp v42, v40 quad_perm:[2,3,0,1] row_mask:0xf bank_mask:0xf bound_ctrl:1
	v_mov_b32_dpp v43, v41 quad_perm:[2,3,0,1] row_mask:0xf bank_mask:0xf bound_ctrl:1
	v_pk_add_f32 v[40:41], v[40:41], v[42:43]
	v_add_f32_dpp v50, v50, v50 quad_perm:[2,3,0,1] row_mask:0xf bank_mask:0xf bound_ctrl:1
	s_nop 0
	v_mov_b32_dpp v42, v40 row_half_mirror row_mask:0xf bank_mask:0xf bound_ctrl:1
	v_mov_b32_dpp v43, v41 row_half_mirror row_mask:0xf bank_mask:0xf bound_ctrl:1
	v_pk_add_f32 v[40:41], v[40:41], v[42:43]
	v_add_f32_dpp v50, v50, v50 row_half_mirror row_mask:0xf bank_mask:0xf bound_ctrl:1
	s_nop 0
	v_mov_b32_dpp v42, v40 row_mirror row_mask:0xf bank_mask:0xf bound_ctrl:1
	v_mov_b32_dpp v43, v41 row_mirror row_mask:0xf bank_mask:0xf bound_ctrl:1
	v_mov_b32_dpp v51, v50 row_mirror row_mask:0xf bank_mask:0xf bound_ctrl:1
	s_and_saveexec_b64 s[6:7], s[92:93]
	s_cbranch_execz .LBB0_169
	v_lshlrev_b32_e32 v54, 16, v82
	v_and_b32_e32 v55, 0xffff0000, v82
	v_lshlrev_b32_e32 v56, 16, v83
	v_and_b32_e32 v57, 0xffff0000, v83
	v_pk_add_f32 v[38:39], v[38:39], v[56:57] neg_lo:[0,1] neg_hi:[0,1]
	v_pk_add_f32 v[36:37], v[36:37], v[54:55] neg_lo:[0,1] neg_hi:[0,1]
	v_add3_u32 v53, v52, v115, v116
	v_pk_fma_f32 v[36:37], v[4:5], v[36:37], v[54:55]
	v_pk_fma_f32 v[38:39], v[6:7], v[38:39], v[56:57]
	ds_write_b128 v53, v[36:39] offset:20480

; __device__ __forceinline__ void gb_step(const u16* ga, const u16* gw, size_t a64, size_t w64, int ko, bool issue, ...
;   if (issue) {
; #pragma unroll
;     for (int i = 0; i < 4; i++)
;       __builtin_amdgcn_global_load_lds((const unsigned*)(ga + i * a64 + ko), (lds_u32*)(wr + (i * 4 + wave) * 512), 16, 0, 0);
; #pragma unroll
;     for (int i = 0; i < 2; i++)
;       __builtin_amdgcn_global_load_lds((const unsigned*)(gw + i * w64 + ko), (lds_u32*)(wr + 256 * GST + (i * 4 + wave) * 512), 16, 0, 0);
;   }
;   const unsigned rdb = (unsigned)(size_t)(__attribute__((address_space(3))) const char*)rd;
;   const unsigned ab = rdb + (unsigned)(((wm * 128 + (lane & 15)) * GST + rsw) * 2);
;   const int wr0 = wn * 64 + (((lane & 15) >> 2) << 3) + (lane & 3);
;   const unsigned bb0 = rdb + (unsigned)((256 * GST + wr0 * GST + GSW(wr0, lane >> 4)) * 2);
;   const unsigned bb1 = rdb + (unsigned)((256 * GST + (wr0 + 4) * GST + GSW(wr0 + 4, lane >> 4)) * 2);
;   bf16x8 wf0, wf1, wf2, wf3, xf0, xf1, xf2, xf3, xf4, xf5, xf6, xf7;
;     ...
;   DSR(wf0, bb0, 0); DSR(wf1, bb1, 0); DSR(wf2, bb0, 2048); DSR(wf3, bb1, 2048);
;   DSR(xf0, ab, 0); DSR(xf1, ab, 1024); DSR(xf2, ab, 2048); DSR(xf3, ab, 3072);
;   DSR(xf4, ab, 4096); DSR(xf5, ab, 5120); DSR(xf6, ab, 6144); DSR(xf7, ab, 7168);
;     ...
;   asm volatile("s_waitcnt lgkmcnt(7)" : "+v"(wf0), "+v"(wf1), "+v"(wf2), "+v"(wf3), "+v"(xf0) : : "memory");
;   MM(0, xf0)
;   asm volatile("s_waitcnt lgkmcnt(6)" : "+v"(xf1) : : "memory");
;   MM(1, xf1)
;   asm volatile("s_waitcnt lgkmcnt(5)" : "+v"(xf2) : : "memory");
;   MM(2, xf2)
;   asm volatile("s_waitcnt lgkmcnt(4)" : "+v"(xf3) : : "memory");
;   MM(3, xf3)
;   asm volatile("s_waitcnt lgkmcnt(3)" : "+v"(xf4) : : "memory");
;   MM(4, xf4)
;   asm volatile("s_waitcnt lgkmcnt(2)" : "+v"(xf5) : : "memory");
;   MM(5, xf5)
;   asm volatile("s_waitcnt lgkmcnt(1)" : "+v"(xf6) : : "memory");
;   MM(6, xf6)
;   asm volatile("s_waitcnt lgkmcnt(0)" : "+v"(xf7) : : "memory");
;   MM(7, xf7)
;     ...
; }
; template <class F>
; __device__ __forceinline__ void gemm_big(const ALbf& al, const u16* __restrict__ Wt, int K, int m0, int n0, const F& f, u16* sm) {
;     ...
;   for (int kt = 0; kt < nk; ++kt) {
;     const int nxt2 = (cur >= 1) ? cur - 1 : 2;
;     gb_step(ga, gw, a64, w64, (kt + 2) * 32, kt + 2 < nk, sm + cur * GB_STAGE_EL, sm + nxt2 * GB_STAGE_EL, wave, wm, wn, lane, rsw, acc);
.Lgz0_mloop:
	v_add_u32_e32 v212, s10, v216
	ds_read_b128 v[252:255], v212 offset:0
	ds_read_b128 v[204:207], v212 offset:512
	ds_read_b128 v[208:211], v212 offset:4096
	ds_read_b128 v[212:215], v212 offset:4608
	v_mfma_f32_16x16x32_bf16 v[124:127], v[236:239], v[144:147], v[124:127]
	ds_read_b128 v[176:179], v219 offset:49152
	v_mfma_f32_16x16x32_bf16 v[120:123], v[240:243], v[144:147], v[120:123]
	ds_read_b128 v[180:183], v219 offset:51200
	v_mfma_f32_16x16x32_bf16 v[92:95], v[244:247], v[144:147], v[92:95]
	ds_read_b128 v[184:187], v219 offset:53248
	v_mfma_f32_16x16x32_bf16 v[88:91], v[248:251], v[144:147], v[88:91]
	ds_read_b128 v[188:191], v219 offset:55296
	v_mfma_f32_16x16x32_bf16 v[116:119], v[236:239], v[148:151], v[116:119]
	ds_read_b128 v[192:195], v228 offset:49152
	v_mfma_f32_16x16x32_bf16 v[112:115], v[240:243], v[148:151], v[112:115]
	ds_read_b128 v[220:223], v228 offset:51200
	v_mfma_f32_16x16x32_bf16 v[76:79], v[244:247], v[148:151], v[76:79]
	ds_read_b128 v[224:227], v228 offset:53248
	v_mfma_f32_16x16x32_bf16 v[72:75], v[248:251], v[148:151], v[72:75]
	ds_read_b128 v[232:235], v228 offset:55296
	s_add_u32 m0, s17, 0x8000
	v_mfma_f32_16x16x32_bf16 v[108:111], v[236:239], v[152:155], v[108:111]
	global_load_lds_dwordx4 v128, s[6:7]
	v_mfma_f32_16x16x32_bf16 v[104:107], v[240:243], v[152:155], v[104:107]
	s_add_u32 m0, s17, 0x9000
	v_mfma_f32_16x16x32_bf16 v[60:63], v[244:247], v[152:155], v[60:63]
	global_load_lds_dwordx4 v129, s[6:7]
	v_mfma_f32_16x16x32_bf16 v[56:59], v[248:251], v[152:155], v[56:59]
	s_add_u32 m0, s17, 0xa000
	v_mfma_f32_16x16x32_bf16 v[100:103], v[236:239], v[156:159], v[100:103]
	global_load_lds_dwordx4 v130, s[6:7]
	v_mfma_f32_16x16x32_bf16 v[96:99], v[240:243], v[156:159], v[96:99]
	s_add_u32 m0, s17, 0xb000
	v_mfma_f32_16x16x32_bf16 v[44:47], v[244:247], v[156:159], v[44:47]
	global_load_lds_dwordx4 v131, s[6:7]
	v_mfma_f32_16x16x32_bf16 v[40:43], v[248:251], v[156:159], v[40:43]
	s_waitcnt lgkmcnt(8)
	v_mfma_f32_16x16x32_bf16 v[124:127], v[252:255], v[160:163], v[124:127]
	v_mfma_f32_16x16x32_bf16 v[120:123], v[204:207], v[160:163], v[120:123]
	v_mfma_f32_16x16x32_bf16 v[92:95], v[208:211], v[160:163], v[92:95]
	v_mfma_f32_16x16x32_bf16 v[88:91], v[212:215], v[160:163], v[88:91]
	v_mfma_f32_16x16x32_bf16 v[116:119], v[252:255], v[164:167], v[116:119]
	v_mfma_f32_16x16x32_bf16 v[112:115], v[204:207], v[164:167], v[112:115]
	v_mfma_f32_16x16x32_bf16 v[76:79], v[208:211], v[164:167], v[76:79]
	v_mfma_f32_16x16x32_bf16 v[72:75], v[212:215], v[164:167], v[72:75]
	v_mfma_f32_16x16x32_bf16 v[108:111], v[252:255], v[168:171], v[108:111]
	v_mfma_f32_16x16x32_bf16 v[104:107], v[204:207], v[168:171], v[104:107]
	v_mfma_f32_16x16x32_bf16 v[60:63], v[208:211], v[168:171], v[60:63]
	v_mfma_f32_16x16x32_bf16 v[56:59], v[212:215], v[168:171], v[56:59]
	v_mfma_f32_16x16x32_bf16 v[100:103], v[252:255], v[172:175], v[100:103]
	v_mfma_f32_16x16x32_bf16 v[96:99], v[204:207], v[172:175], v[96:99]
	v_mfma_f32_16x16x32_bf16 v[44:47], v[208:211], v[172:175], v[44:47]
	v_mfma_f32_16x16x32_bf16 v[40:43], v[212:215], v[172:175], v[40:43]
	s_waitcnt vmcnt(0)
	s_waitcnt lgkmcnt(0)
	s_add_u32 s6, s6, 0x20000
	s_addc_u32 s7, s7, 0
	s_xor_b32 s11, s10, 0x4000
	s_barrier
	v_mfma_f32_16x16x32_bf16 v[84:87], v[236:239], v[176:179], v[84:87]
	ds_read_b128 v[144:147], v219 offset:32768
	v_mfma_f32_16x16x32_bf16 v[80:83], v[240:243], v[176:179], v[80:83]
	ds_read_b128 v[148:151], v219 offset:34816
	v_mfma_f32_16x16x32_bf16 v[28:31], v[244:247], v[176:179], v[28:31]
	ds_read_b128 v[152:155], v219 offset:36864
	v_mfma_f32_16x16x32_bf16 v[24:27], v[248:251], v[176:179], v[24:27]
	ds_read_b128 v[156:159], v219 offset:38912
	v_mfma_f32_16x16x32_bf16 v[68:71], v[236:239], v[180:183], v[68:71]
	ds_read_b128 v[160:163], v228 offset:32768
	v_mfma_f32_16x16x32_bf16 v[64:67], v[240:243], v[180:183], v[64:67]
	ds_read_b128 v[164:167], v228 offset:34816
	v_mfma_f32_16x16x32_bf16 v[20:23], v[244:247], v[180:183], v[20:23]
	ds_read_b128 v[168:171], v228 offset:36864
	v_mfma_f32_16x16x32_bf16 v[16:19], v[248:251], v[180:183], v[16:19]
	ds_read_b128 v[172:175], v228 offset:38912
	s_add_u32 m0, s17, 0xc000
	v_mfma_f32_16x16x32_bf16 v[52:55], v[236:239], v[184:187], v[52:55]
	global_load_lds_dwordx4 v128, s[6:7]
	v_mfma_f32_16x16x32_bf16 v[48:51], v[240:243], v[184:187], v[48:51]
	s_add_u32 m0, s17, 0xd000
	v_mfma_f32_16x16x32_bf16 v[12:15], v[244:247], v[184:187], v[12:15]
	global_load_lds_dwordx4 v129, s[6:7]
	v_mfma_f32_16x16x32_bf16 v[8:11], v[248:251], v[184:187], v[8:11]
	s_add_u32 m0, s17, 0xe000
	v_mfma_f32_16x16x32_bf16 v[36:39], v[236:239], v[188:191], v[36:39]
	global_load_lds_dwordx4 v130, s[6:7]
	v_mfma_f32_16x16x32_bf16 v[32:35], v[240:243], v[188:191], v[32:35]
	s_add_u32 m0, s17, 0xf000
	v_mfma_f32_16x16x32_bf16 v[4:7], v[244:247], v[188:191], v[4:7]
	global_load_lds_dwordx4 v131, s[6:7]
	v_mfma_f32_16x16x32_bf16 v[0:3], v[248:251], v[188:191], v[0:3]
	v_add_u32_e32 v248, s11, v231
	v_mfma_f32_16x16x32_bf16 v[84:87], v[252:255], v[192:195], v[84:87]
	ds_read_b128 v[236:239], v248 offset:0
	v_mfma_f32_16x16x32_bf16 v[80:83], v[204:207], v[192:195], v[80:83]
	ds_read_b128 v[240:243], v248 offset:512
	v_mfma_f32_16x16x32_bf16 v[28:31], v[208:211], v[192:195], v[28:31]
	ds_read_b128 v[244:247], v248 offset:4096
	v_mfma_f32_16x16x32_bf16 v[24:27], v[212:215], v[192:195], v[24:27]
	ds_read_b128 v[248:251], v248 offset:4608
	v_mfma_f32_16x16x32_bf16 v[68:71], v[252:255], v[220:223], v[68:71]
	v_mfma_f32_16x16x32_bf16 v[64:67], v[204:207], v[220:223], v[64:67]
	s_add_u32 m0, s17, s10
	s_add_u32 m0, m0, 0x0
	s_nop 0
	global_load_lds_dwordx4 v134, s[8:9]
	v_mfma_f32_16x16x32_bf16 v[20:23], v[208:211], v[220:223], v[20:23]
	v_mfma_f32_16x16x32_bf16 v[16:19], v[212:215], v[220:223], v[16:19]
	s_add_u32 m0, s17, s10
	s_add_u32 m0, m0, 0x1000
	s_nop 0
	global_load_lds_dwordx4 v143, s[8:9]
	v_mfma_f32_16x16x32_bf16 v[52:55], v[252:255], v[224:227], v[52:55]
	v_mfma_f32_16x16x32_bf16 v[48:51], v[204:207], v[224:227], v[48:51]
	s_add_u32 m0, s17, s10
	s_add_u32 m0, m0, 0x2000
	s_nop 0
	global_load_lds_dwordx4 v196, s[8:9]
	v_mfma_f32_16x16x32_bf16 v[12:15], v[208:211], v[224:227], v[12:15]
	v_mfma_f32_16x16x32_bf16 v[8:11], v[212:215], v[224:227], v[8:11]
	s_add_u32 m0, s17, s10
	s_add_u32 m0, m0, 0x3000
	s_nop 0
	global_load_lds_dwordx4 v197, s[8:9]
	v_mfma_f32_16x16x32_bf16 v[36:39], v[252:255], v[232:235], v[36:39]
	v_mfma_f32_16x16x32_bf16 v[32:35], v[204:207], v[232:235], v[32:35]
	v_mfma_f32_16x16x32_bf16 v[4:7], v[208:211], v[232:235], v[4:7]
	v_mfma_f32_16x16x32_bf16 v[0:3], v[212:215], v[232:235], v[0:3]
	s_waitcnt vmcnt(4)
	s_waitcnt lgkmcnt(0)
	s_add_u32 s6, s6, 0xfffe0080
	s_addc_u32 s7, s7, -1
	s_add_u32 s8, s8, 0x80
	s_addc_u32 s9, s9, 0
	s_mov_b32 s10, s11
	s_add_u32 s16, s16, 1
	s_cmp_lt_u32 s16, 14
	s_barrier
	s_cbranch_scc1 .Lgz0_mloop

; __device__ __forceinline__ void gb_step(const u16* ga, const u16* gw, size_t a64, size_t w64, int ko, bool issue, ...
;   if (issue) {
; #pragma unroll
;     for (int i = 0; i < 4; i++)
;       __builtin_amdgcn_global_load_lds((const unsigned*)(ga + i * a64 + ko), (lds_u32*)(wr + (i * 4 + wave) * 512), 16, 0, 0);
; #pragma unroll
;     for (int i = 0; i < 2; i++)
;       __builtin_amdgcn_global_load_lds((const unsigned*)(gw + i * w64 + ko), (lds_u32*)(wr + 256 * GST + (i * 4 + wave) * 512), 16, 0, 0);
;   }
;   const unsigned rdb = (unsigned)(size_t)(__attribute__((address_space(3))) const char*)rd;
;   const unsigned ab = rdb + (unsigned)(((wm * 128 + (lane & 15)) * GST + rsw) * 2);
;   const int wr0 = wn * 64 + (((lane & 15) >> 2) << 3) + (lane & 3);
;   const unsigned bb0 = rdb + (unsigned)((256 * GST + wr0 * GST + GSW(wr0, lane >> 4)) * 2);
;   const unsigned bb1 = rdb + (unsigned)((256 * GST + (wr0 + 4) * GST + GSW(wr0 + 4, lane >> 4)) * 2);
;   bf16x8 wf0, wf1, wf2, wf3, xf0, xf1, xf2, xf3, xf4, xf5, xf6, xf7;
;     ...
;   DSR(wf0, bb0, 0); DSR(wf1, bb1, 0); DSR(wf2, bb0, 2048); DSR(wf3, bb1, 2048);
;   DSR(xf0, ab, 0); DSR(xf1, ab, 1024); DSR(xf2, ab, 2048); DSR(xf3, ab, 3072);
;   DSR(xf4, ab, 4096); DSR(xf5, ab, 5120); DSR(xf6, ab, 6144); DSR(xf7, ab, 7168);
;     ...
;   asm volatile("s_waitcnt lgkmcnt(7)" : "+v"(wf0), "+v"(wf1), "+v"(wf2), "+v"(wf3), "+v"(xf0) : : "memory");
;   MM(0, xf0)
;   asm volatile("s_waitcnt lgkmcnt(6)" : "+v"(xf1) : : "memory");
;   MM(1, xf1)
;   asm volatile("s_waitcnt lgkmcnt(5)" : "+v"(xf2) : : "memory");
;   MM(2, xf2)
;   asm volatile("s_waitcnt lgkmcnt(4)" : "+v"(xf3) : : "memory");
;   MM(3, xf3)
;   asm volatile("s_waitcnt lgkmcnt(3)" : "+v"(xf4) : : "memory");
;   MM(4, xf4)
;   asm volatile("s_waitcnt lgkmcnt(2)" : "+v"(xf5) : : "memory");
;   MM(5, xf5)
;   asm volatile("s_waitcnt lgkmcnt(1)" : "+v"(xf6) : : "memory");
;   MM(6, xf6)
;   asm volatile("s_waitcnt lgkmcnt(0)" : "+v"(xf7) : : "memory");
;   MM(7, xf7)
;     ...
; }
; template <class F>
; __device__ __forceinline__ void gemm_big(const ALbf& al, const u16* __restrict__ Wt, int K, int m0, int n0, const F& f, u16* sm) {
;     ...
;   for (int kt = 0; kt < nk; ++kt) {
;     const int nxt2 = (cur >= 1) ? cur - 1 : 2;
;     gb_step(ga, gw, a64, w64, (kt + 2) * 32, kt + 2 < nk, sm + cur * GB_STAGE_EL, sm + nxt2 * GB_STAGE_EL, wave, wm, wn, lane, rsw, acc);
.Lgz1_mloop:
	v_add_u32_e32 v212, s14, v216
	ds_read_b128 v[252:255], v212 offset:0
	ds_read_b128 v[204:207], v212 offset:512
	ds_read_b128 v[208:211], v212 offset:4096
	ds_read_b128 v[212:215], v212 offset:4608
	v_mfma_f32_16x16x32_bf16 v[124:127], v[236:239], v[144:147], v[124:127]
	ds_read_b128 v[176:179], v219 offset:49152
	v_mfma_f32_16x16x32_bf16 v[120:123], v[240:243], v[144:147], v[120:123]
	ds_read_b128 v[180:183], v219 offset:51200
	v_mfma_f32_16x16x32_bf16 v[76:79], v[244:247], v[144:147], v[76:79]
	ds_read_b128 v[184:187], v219 offset:53248
	v_mfma_f32_16x16x32_bf16 v[68:71], v[248:251], v[144:147], v[68:71]
	ds_read_b128 v[188:191], v219 offset:55296
	v_mfma_f32_16x16x32_bf16 v[116:119], v[236:239], v[148:151], v[116:119]
	ds_read_b128 v[192:195], v228 offset:49152
	v_mfma_f32_16x16x32_bf16 v[112:115], v[240:243], v[148:151], v[112:115]
	ds_read_b128 v[220:223], v228 offset:51200
	v_mfma_f32_16x16x32_bf16 v[60:63], v[244:247], v[148:151], v[60:63]
	ds_read_b128 v[224:227], v228 offset:53248
	v_mfma_f32_16x16x32_bf16 v[56:59], v[248:251], v[148:151], v[56:59]
	ds_read_b128 v[232:235], v228 offset:55296
	s_add_u32 m0, s95, 0x8000
	v_mfma_f32_16x16x32_bf16 v[108:111], v[236:239], v[152:155], v[108:111]
	global_load_lds_dwordx4 v128, s[10:11]
	v_mfma_f32_16x16x32_bf16 v[104:107], v[240:243], v[152:155], v[104:107]
	s_add_u32 m0, s95, 0x9000
	v_mfma_f32_16x16x32_bf16 v[44:47], v[244:247], v[152:155], v[44:47]
	global_load_lds_dwordx4 v129, s[10:11]
	v_mfma_f32_16x16x32_bf16 v[40:43], v[248:251], v[152:155], v[40:43]
	s_add_u32 m0, s95, 0xa000
	v_mfma_f32_16x16x32_bf16 v[100:103], v[236:239], v[156:159], v[100:103]
	global_load_lds_dwordx4 v130, s[10:11]
	v_mfma_f32_16x16x32_bf16 v[96:99], v[240:243], v[156:159], v[96:99]
	s_add_u32 m0, s95, 0xb000
	v_mfma_f32_16x16x32_bf16 v[36:39], v[244:247], v[156:159], v[36:39]
	global_load_lds_dwordx4 v131, s[10:11]
	v_mfma_f32_16x16x32_bf16 v[32:35], v[248:251], v[156:159], v[32:35]
	s_waitcnt lgkmcnt(8)
	v_mfma_f32_16x16x32_bf16 v[124:127], v[252:255], v[160:163], v[124:127]
	v_mfma_f32_16x16x32_bf16 v[120:123], v[204:207], v[160:163], v[120:123]
	v_mfma_f32_16x16x32_bf16 v[76:79], v[208:211], v[160:163], v[76:79]
	v_mfma_f32_16x16x32_bf16 v[68:71], v[212:215], v[160:163], v[68:71]
	v_mfma_f32_16x16x32_bf16 v[116:119], v[252:255], v[164:167], v[116:119]
	v_mfma_f32_16x16x32_bf16 v[112:115], v[204:207], v[164:167], v[112:115]
	v_mfma_f32_16x16x32_bf16 v[60:63], v[208:211], v[164:167], v[60:63]
	v_mfma_f32_16x16x32_bf16 v[56:59], v[212:215], v[164:167], v[56:59]
	v_mfma_f32_16x16x32_bf16 v[108:111], v[252:255], v[168:171], v[108:111]
	v_mfma_f32_16x16x32_bf16 v[104:107], v[204:207], v[168:171], v[104:107]
	v_mfma_f32_16x16x32_bf16 v[44:47], v[208:211], v[168:171], v[44:47]
	v_mfma_f32_16x16x32_bf16 v[40:43], v[212:215], v[168:171], v[40:43]
	v_mfma_f32_16x16x32_bf16 v[100:103], v[252:255], v[172:175], v[100:103]
	v_mfma_f32_16x16x32_bf16 v[96:99], v[204:207], v[172:175], v[96:99]
	v_mfma_f32_16x16x32_bf16 v[36:39], v[208:211], v[172:175], v[36:39]
	v_mfma_f32_16x16x32_bf16 v[32:35], v[212:215], v[172:175], v[32:35]
	s_waitcnt vmcnt(0)
	s_waitcnt lgkmcnt(0)
	s_add_u32 s10, s10, 0x20000
	s_addc_u32 s11, s11, 0
	s_xor_b32 s15, s14, 0x4000
	s_barrier
	v_mfma_f32_16x16x32_bf16 v[92:95], v[236:239], v[176:179], v[92:95]
	ds_read_b128 v[144:147], v219 offset:32768
	v_mfma_f32_16x16x32_bf16 v[88:91], v[240:243], v[176:179], v[88:91]
	ds_read_b128 v[148:151], v219 offset:34816
	v_mfma_f32_16x16x32_bf16 v[28:31], v[244:247], v[176:179], v[28:31]
	ds_read_b128 v[152:155], v219 offset:36864
	v_mfma_f32_16x16x32_bf16 v[24:27], v[248:251], v[176:179], v[24:27]
	ds_read_b128 v[156:159], v219 offset:38912
	v_mfma_f32_16x16x32_bf16 v[84:87], v[236:239], v[180:183], v[84:87]
	ds_read_b128 v[160:163], v228 offset:32768
	v_mfma_f32_16x16x32_bf16 v[80:83], v[240:243], v[180:183], v[80:83]
	ds_read_b128 v[164:167], v228 offset:34816
	v_mfma_f32_16x16x32_bf16 v[20:23], v[244:247], v[180:183], v[20:23]
	ds_read_b128 v[168:171], v228 offset:36864
	v_mfma_f32_16x16x32_bf16 v[16:19], v[248:251], v[180:183], v[16:19]
	ds_read_b128 v[172:175], v228 offset:38912
	s_add_u32 m0, s95, 0xc000
	v_mfma_f32_16x16x32_bf16 v[72:75], v[236:239], v[184:187], v[72:75]
	global_load_lds_dwordx4 v128, s[10:11]
	v_mfma_f32_16x16x32_bf16 v[64:67], v[240:243], v[184:187], v[64:67]
	s_add_u32 m0, s95, 0xd000
	v_mfma_f32_16x16x32_bf16 v[12:15], v[244:247], v[184:187], v[12:15]
	global_load_lds_dwordx4 v129, s[10:11]
	v_mfma_f32_16x16x32_bf16 v[8:11], v[248:251], v[184:187], v[8:11]
	s_add_u32 m0, s95, 0xe000
	v_mfma_f32_16x16x32_bf16 v[52:55], v[236:239], v[188:191], v[52:55]
	global_load_lds_dwordx4 v130, s[10:11]
	v_mfma_f32_16x16x32_bf16 v[48:51], v[240:243], v[188:191], v[48:51]
	s_add_u32 m0, s95, 0xf000
	v_mfma_f32_16x16x32_bf16 v[4:7], v[244:247], v[188:191], v[4:7]
	global_load_lds_dwordx4 v131, s[10:11]
	v_mfma_f32_16x16x32_bf16 v[0:3], v[248:251], v[188:191], v[0:3]
	v_add_u32_e32 v248, s15, v231
	v_mfma_f32_16x16x32_bf16 v[92:95], v[252:255], v[192:195], v[92:95]
	ds_read_b128 v[236:239], v248 offset:0
	v_mfma_f32_16x16x32_bf16 v[88:91], v[204:207], v[192:195], v[88:91]
	ds_read_b128 v[240:243], v248 offset:512
	v_mfma_f32_16x16x32_bf16 v[28:31], v[208:211], v[192:195], v[28:31]
	ds_read_b128 v[244:247], v248 offset:4096
	v_mfma_f32_16x16x32_bf16 v[24:27], v[212:215], v[192:195], v[24:27]
	ds_read_b128 v[248:251], v248 offset:4608
	v_mfma_f32_16x16x32_bf16 v[84:87], v[252:255], v[220:223], v[84:87]
	v_mfma_f32_16x16x32_bf16 v[80:83], v[204:207], v[220:223], v[80:83]
	s_add_u32 m0, s95, s14
	s_add_u32 m0, m0, 0x0
	s_nop 0
	global_load_lds_dwordx4 v134, s[12:13]
	v_mfma_f32_16x16x32_bf16 v[20:23], v[208:211], v[220:223], v[20:23]
	v_mfma_f32_16x16x32_bf16 v[16:19], v[212:215], v[220:223], v[16:19]
	s_add_u32 m0, s95, s14
	s_add_u32 m0, m0, 0x1000
	s_nop 0
	global_load_lds_dwordx4 v143, s[12:13]
	v_mfma_f32_16x16x32_bf16 v[72:75], v[252:255], v[224:227], v[72:75]
	v_mfma_f32_16x16x32_bf16 v[64:67], v[204:207], v[224:227], v[64:67]
	s_add_u32 m0, s95, s14
	s_add_u32 m0, m0, 0x2000
	s_nop 0
	global_load_lds_dwordx4 v196, s[12:13]
	v_mfma_f32_16x16x32_bf16 v[12:15], v[208:211], v[224:227], v[12:15]
	v_mfma_f32_16x16x32_bf16 v[8:11], v[212:215], v[224:227], v[8:11]
	s_add_u32 m0, s95, s14
	s_add_u32 m0, m0, 0x3000
	s_nop 0
	global_load_lds_dwordx4 v197, s[12:13]
	v_mfma_f32_16x16x32_bf16 v[52:55], v[252:255], v[232:235], v[52:55]
	v_mfma_f32_16x16x32_bf16 v[48:51], v[204:207], v[232:235], v[48:51]
	v_mfma_f32_16x16x32_bf16 v[4:7], v[208:211], v[232:235], v[4:7]
	v_mfma_f32_16x16x32_bf16 v[0:3], v[212:215], v[232:235], v[0:3]
	s_waitcnt vmcnt(4)
	s_waitcnt lgkmcnt(0)
	s_add_u32 s10, s10, 0xfffe0080
	s_addc_u32 s11, s11, -1
	s_add_u32 s12, s12, 0x80
	s_addc_u32 s13, s13, 0
	s_mov_b32 s14, s15
	s_add_u32 s94, s94, 1
	s_cmp_lt_u32 s94, 14
	s_barrier
	s_cbranch_scc1 .Lgz1_mloop

; __device__ __forceinline__ void gb_step(const u16* ga, const u16* gw, size_t a64, size_t w64, int ko, bool issue, ...
;   if (issue) {
; #pragma unroll
;     for (int i = 0; i < 4; i++)
;       __builtin_amdgcn_global_load_lds((const unsigned*)(ga + i * a64 + ko), (lds_u32*)(wr + (i * 4 + wave) * 512), 16, 0, 0);
; #pragma unroll
;     for (int i = 0; i < 2; i++)
;       __builtin_amdgcn_global_load_lds((const unsigned*)(gw + i * w64 + ko), (lds_u32*)(wr + 256 * GST + (i * 4 + wave) * 512), 16, 0, 0);
;   }
;   const unsigned rdb = (unsigned)(size_t)(__attribute__((address_space(3))) const char*)rd;
;   const unsigned ab = rdb + (unsigned)(((wm * 128 + (lane & 15)) * GST + rsw) * 2);
;   const int wr0 = wn * 64 + (((lane & 15) >> 2) << 3) + (lane & 3);
;   const unsigned bb0 = rdb + (unsigned)((256 * GST + wr0 * GST + GSW(wr0, lane >> 4)) * 2);
;   const unsigned bb1 = rdb + (unsigned)((256 * GST + (wr0 + 4) * GST + GSW(wr0 + 4, lane >> 4)) * 2);
;   bf16x8 wf0, wf1, wf2, wf3, xf0, xf1, xf2, xf3, xf4, xf5, xf6, xf7;
;     ...
;   DSR(wf0, bb0, 0); DSR(wf1, bb1, 0); DSR(wf2, bb0, 2048); DSR(wf3, bb1, 2048);
;   DSR(xf0, ab, 0); DSR(xf1, ab, 1024); DSR(xf2, ab, 2048); DSR(xf3, ab, 3072);
;   DSR(xf4, ab, 4096); DSR(xf5, ab, 5120); DSR(xf6, ab, 6144); DSR(xf7, ab, 7168);
;     ...
;   asm volatile("s_waitcnt lgkmcnt(7)" : "+v"(wf0), "+v"(wf1), "+v"(wf2), "+v"(wf3), "+v"(xf0) : : "memory");
;   MM(0, xf0)
;   asm volatile("s_waitcnt lgkmcnt(6)" : "+v"(xf1) : : "memory");
;   MM(1, xf1)
;   asm volatile("s_waitcnt lgkmcnt(5)" : "+v"(xf2) : : "memory");
;   MM(2, xf2)
;   asm volatile("s_waitcnt lgkmcnt(4)" : "+v"(xf3) : : "memory");
;   MM(3, xf3)
;   asm volatile("s_waitcnt lgkmcnt(3)" : "+v"(xf4) : : "memory");
;   MM(4, xf4)
;   asm volatile("s_waitcnt lgkmcnt(2)" : "+v"(xf5) : : "memory");
;   MM(5, xf5)
;   asm volatile("s_waitcnt lgkmcnt(1)" : "+v"(xf6) : : "memory");
;   MM(6, xf6)
;   asm volatile("s_waitcnt lgkmcnt(0)" : "+v"(xf7) : : "memory");
;   MM(7, xf7)
;     ...
; }
; template <class F>
; __device__ __forceinline__ void gemm_big(const ALbf& al, const u16* __restrict__ Wt, int K, int m0, int n0, const F& f, u16* sm) {
;     ...
;   for (int kt = 0; kt < nk; ++kt) {
;     const int nxt2 = (cur >= 1) ? cur - 1 : 2;
;     gb_step(ga, gw, a64, w64, (kt + 2) * 32, kt + 2 < nk, sm + cur * GB_STAGE_EL, sm + nxt2 * GB_STAGE_EL, wave, wm, wn, lane, rsw, acc);
.Lgz2_mloop:
	v_add_u32_e32 v212, s14, v216
	ds_read_b128 v[252:255], v212 offset:0
	ds_read_b128 v[204:207], v212 offset:512
	ds_read_b128 v[208:211], v212 offset:4096
	ds_read_b128 v[212:215], v212 offset:4608
	v_mfma_f32_16x16x32_bf16 v[124:127], v[236:239], v[144:147], v[124:127]
	ds_read_b128 v[176:179], v219 offset:49152
	v_mfma_f32_16x16x32_bf16 v[120:123], v[240:243], v[144:147], v[120:123]
	ds_read_b128 v[180:183], v219 offset:51200
	v_mfma_f32_16x16x32_bf16 v[84:87], v[244:247], v[144:147], v[84:87]
	ds_read_b128 v[184:187], v219 offset:53248
	v_mfma_f32_16x16x32_bf16 v[80:83], v[248:251], v[144:147], v[80:83]
	ds_read_b128 v[188:191], v219 offset:55296
	v_mfma_f32_16x16x32_bf16 v[116:119], v[236:239], v[148:151], v[116:119]
	ds_read_b128 v[192:195], v228 offset:49152
	v_mfma_f32_16x16x32_bf16 v[112:115], v[240:243], v[148:151], v[112:115]
	ds_read_b128 v[220:223], v228 offset:51200
	v_mfma_f32_16x16x32_bf16 v[76:79], v[244:247], v[148:151], v[76:79]
	ds_read_b128 v[224:227], v228 offset:53248
	v_mfma_f32_16x16x32_bf16 v[68:71], v[248:251], v[148:151], v[68:71]
	ds_read_b128 v[232:235], v228 offset:55296
	s_add_u32 m0, s95, 0x8000
	v_mfma_f32_16x16x32_bf16 v[108:111], v[236:239], v[152:155], v[108:111]
	global_load_lds_dwordx4 v128, s[10:11]
	v_mfma_f32_16x16x32_bf16 v[104:107], v[240:243], v[152:155], v[104:107]
	s_add_u32 m0, s95, 0x9000
	v_mfma_f32_16x16x32_bf16 v[60:63], v[244:247], v[152:155], v[60:63]
	global_load_lds_dwordx4 v129, s[10:11]
	v_mfma_f32_16x16x32_bf16 v[56:59], v[248:251], v[152:155], v[56:59]
	s_add_u32 m0, s95, 0xa000
	v_mfma_f32_16x16x32_bf16 v[100:103], v[236:239], v[156:159], v[100:103]
	global_load_lds_dwordx4 v130, s[10:11]
	v_mfma_f32_16x16x32_bf16 v[96:99], v[240:243], v[156:159], v[96:99]
	s_add_u32 m0, s95, 0xb000
	v_mfma_f32_16x16x32_bf16 v[44:47], v[244:247], v[156:159], v[44:47]
	global_load_lds_dwordx4 v131, s[10:11]
	v_mfma_f32_16x16x32_bf16 v[40:43], v[248:251], v[156:159], v[40:43]
	s_waitcnt lgkmcnt(8)
	v_mfma_f32_16x16x32_bf16 v[124:127], v[252:255], v[160:163], v[124:127]
	v_mfma_f32_16x16x32_bf16 v[120:123], v[204:207], v[160:163], v[120:123]
	v_mfma_f32_16x16x32_bf16 v[84:87], v[208:211], v[160:163], v[84:87]
	v_mfma_f32_16x16x32_bf16 v[80:83], v[212:215], v[160:163], v[80:83]
	v_mfma_f32_16x16x32_bf16 v[116:119], v[252:255], v[164:167], v[116:119]
	v_mfma_f32_16x16x32_bf16 v[112:115], v[204:207], v[164:167], v[112:115]
	v_mfma_f32_16x16x32_bf16 v[76:79], v[208:211], v[164:167], v[76:79]
	v_mfma_f32_16x16x32_bf16 v[68:71], v[212:215], v[164:167], v[68:71]
	v_mfma_f32_16x16x32_bf16 v[108:111], v[252:255], v[168:171], v[108:111]
	v_mfma_f32_16x16x32_bf16 v[104:107], v[204:207], v[168:171], v[104:107]
	v_mfma_f32_16x16x32_bf16 v[60:63], v[208:211], v[168:171], v[60:63]
	v_mfma_f32_16x16x32_bf16 v[56:59], v[212:215], v[168:171], v[56:59]
	v_mfma_f32_16x16x32_bf16 v[100:103], v[252:255], v[172:175], v[100:103]
	v_mfma_f32_16x16x32_bf16 v[96:99], v[204:207], v[172:175], v[96:99]
	v_mfma_f32_16x16x32_bf16 v[44:47], v[208:211], v[172:175], v[44:47]
	v_mfma_f32_16x16x32_bf16 v[40:43], v[212:215], v[172:175], v[40:43]
	s_waitcnt vmcnt(0)
	s_waitcnt lgkmcnt(0)
	s_add_u32 s10, s10, 0x80000
	s_addc_u32 s11, s11, 0
	s_xor_b32 s15, s14, 0x4000
	s_barrier
	v_mfma_f32_16x16x32_bf16 v[92:95], v[236:239], v[176:179], v[92:95]
	ds_read_b128 v[144:147], v219 offset:32768
	v_mfma_f32_16x16x32_bf16 v[88:91], v[240:243], v[176:179], v[88:91]
	ds_read_b128 v[148:151], v219 offset:34816
	v_mfma_f32_16x16x32_bf16 v[28:31], v[244:247], v[176:179], v[28:31]
	ds_read_b128 v[152:155], v219 offset:36864
	v_mfma_f32_16x16x32_bf16 v[24:27], v[248:251], v[176:179], v[24:27]
	ds_read_b128 v[156:159], v219 offset:38912
	v_mfma_f32_16x16x32_bf16 v[72:75], v[236:239], v[180:183], v[72:75]
	ds_read_b128 v[160:163], v228 offset:32768
	v_mfma_f32_16x16x32_bf16 v[64:67], v[240:243], v[180:183], v[64:67]
	ds_read_b128 v[164:167], v228 offset:34816
	v_mfma_f32_16x16x32_bf16 v[20:23], v[244:247], v[180:183], v[20:23]
	ds_read_b128 v[168:171], v228 offset:36864
	v_mfma_f32_16x16x32_bf16 v[16:19], v[248:251], v[180:183], v[16:19]
	ds_read_b128 v[172:175], v228 offset:38912
	s_add_u32 m0, s95, 0xc000
	v_mfma_f32_16x16x32_bf16 v[52:55], v[236:239], v[184:187], v[52:55]
	global_load_lds_dwordx4 v128, s[10:11]
	v_mfma_f32_16x16x32_bf16 v[48:51], v[240:243], v[184:187], v[48:51]
	s_add_u32 m0, s95, 0xd000
	v_mfma_f32_16x16x32_bf16 v[12:15], v[244:247], v[184:187], v[12:15]
	global_load_lds_dwordx4 v129, s[10:11]
	v_mfma_f32_16x16x32_bf16 v[8:11], v[248:251], v[184:187], v[8:11]
	s_add_u32 m0, s95, 0xe000
	v_mfma_f32_16x16x32_bf16 v[36:39], v[236:239], v[188:191], v[36:39]
	global_load_lds_dwordx4 v130, s[10:11]
	v_mfma_f32_16x16x32_bf16 v[32:35], v[240:243], v[188:191], v[32:35]
	s_add_u32 m0, s95, 0xf000
	v_mfma_f32_16x16x32_bf16 v[4:7], v[244:247], v[188:191], v[4:7]
	global_load_lds_dwordx4 v131, s[10:11]
	v_mfma_f32_16x16x32_bf16 v[0:3], v[248:251], v[188:191], v[0:3]
	v_add_u32_e32 v248, s15, v231
	v_mfma_f32_16x16x32_bf16 v[92:95], v[252:255], v[192:195], v[92:95]
	ds_read_b128 v[236:239], v248 offset:0
	v_mfma_f32_16x16x32_bf16 v[88:91], v[204:207], v[192:195], v[88:91]
	ds_read_b128 v[240:243], v248 offset:512
	v_mfma_f32_16x16x32_bf16 v[28:31], v[208:211], v[192:195], v[28:31]
	ds_read_b128 v[244:247], v248 offset:4096
	v_mfma_f32_16x16x32_bf16 v[24:27], v[212:215], v[192:195], v[24:27]
	ds_read_b128 v[248:251], v248 offset:4608
	v_mfma_f32_16x16x32_bf16 v[72:75], v[252:255], v[220:223], v[72:75]
	v_mfma_f32_16x16x32_bf16 v[64:67], v[204:207], v[220:223], v[64:67]
	s_add_u32 m0, s95, s14
	s_add_u32 m0, m0, 0x0
	s_nop 0
	global_load_lds_dwordx4 v134, s[12:13]
	v_mfma_f32_16x16x32_bf16 v[20:23], v[208:211], v[220:223], v[20:23]
	v_mfma_f32_16x16x32_bf16 v[16:19], v[212:215], v[220:223], v[16:19]
	s_add_u32 m0, s95, s14
	s_add_u32 m0, m0, 0x1000
	s_nop 0
	global_load_lds_dwordx4 v143, s[12:13]
	v_mfma_f32_16x16x32_bf16 v[52:55], v[252:255], v[224:227], v[52:55]
	v_mfma_f32_16x16x32_bf16 v[48:51], v[204:207], v[224:227], v[48:51]
	s_add_u32 m0, s95, s14
	s_add_u32 m0, m0, 0x2000
	s_nop 0
	global_load_lds_dwordx4 v196, s[12:13]
	v_mfma_f32_16x16x32_bf16 v[12:15], v[208:211], v[224:227], v[12:15]
	v_mfma_f32_16x16x32_bf16 v[8:11], v[212:215], v[224:227], v[8:11]
	s_add_u32 m0, s95, s14
	s_add_u32 m0, m0, 0x3000
	s_nop 0
	global_load_lds_dwordx4 v197, s[12:13]
	v_mfma_f32_16x16x32_bf16 v[36:39], v[252:255], v[232:235], v[36:39]
	v_mfma_f32_16x16x32_bf16 v[32:35], v[204:207], v[232:235], v[32:35]
	v_mfma_f32_16x16x32_bf16 v[4:7], v[208:211], v[232:235], v[4:7]
	v_mfma_f32_16x16x32_bf16 v[0:3], v[212:215], v[232:235], v[0:3]
	s_waitcnt vmcnt(4)
	s_waitcnt lgkmcnt(0)
	s_add_u32 s10, s10, 0xfff80080
	s_addc_u32 s11, s11, -1
	s_add_u32 s12, s12, 0x80
	s_addc_u32 s13, s13, 0
	s_mov_b32 s14, s15
	s_add_u32 s94, s94, 1
	s_cmp_lt_u32 s94, 62
	s_barrier
	s_cbranch_scc1 .Lgz2_mloop

; __device__ __forceinline__ void gb_step(const u16* ga, const u16* gw, size_t a64, size_t w64, int ko, bool issue, ...
;   if (issue) {
; #pragma unroll
;     for (int i = 0; i < 4; i++)
;       __builtin_amdgcn_global_load_lds((const unsigned*)(ga + i * a64 + ko), (lds_u32*)(wr + (i * 4 + wave) * 512), 16, 0, 0);
; #pragma unroll
;     for (int i = 0; i < 2; i++)
;       __builtin_amdgcn_global_load_lds((const unsigned*)(gw + i * w64 + ko), (lds_u32*)(wr + 256 * GST + (i * 4 + wave) * 512), 16, 0, 0);
;   }
;   const unsigned rdb = (unsigned)(size_t)(__attribute__((address_space(3))) const char*)rd;
;   const unsigned ab = rdb + (unsigned)(((wm * 128 + (lane & 15)) * GST + rsw) * 2);
;   const int wr0 = wn * 64 + (((lane & 15) >> 2) << 3) + (lane & 3);
;   const unsigned bb0 = rdb + (unsigned)((256 * GST + wr0 * GST + GSW(wr0, lane >> 4)) * 2);
;   const unsigned bb1 = rdb + (unsigned)((256 * GST + (wr0 + 4) * GST + GSW(wr0 + 4, lane >> 4)) * 2);
;   bf16x8 wf0, wf1, wf2, wf3, xf0, xf1, xf2, xf3, xf4, xf5, xf6, xf7;
;     ...
;   DSR(wf0, bb0, 0); DSR(wf1, bb1, 0); DSR(wf2, bb0, 2048); DSR(wf3, bb1, 2048);
;   DSR(xf0, ab, 0); DSR(xf1, ab, 1024); DSR(xf2, ab, 2048); DSR(xf3, ab, 3072);
;   DSR(xf4, ab, 4096); DSR(xf5, ab, 5120); DSR(xf6, ab, 6144); DSR(xf7, ab, 7168);
;     ...
;   asm volatile("s_waitcnt lgkmcnt(7)" : "+v"(wf0), "+v"(wf1), "+v"(wf2), "+v"(wf3), "+v"(xf0) : : "memory");
;   MM(0, xf0)
;   asm volatile("s_waitcnt lgkmcnt(6)" : "+v"(xf1) : : "memory");
;   MM(1, xf1)
;   asm volatile("s_waitcnt lgkmcnt(5)" : "+v"(xf2) : : "memory");
;   MM(2, xf2)
;   asm volatile("s_waitcnt lgkmcnt(4)" : "+v"(xf3) : : "memory");
;   MM(3, xf3)
;   asm volatile("s_waitcnt lgkmcnt(3)" : "+v"(xf4) : : "memory");
;   MM(4, xf4)
;   asm volatile("s_waitcnt lgkmcnt(2)" : "+v"(xf5) : : "memory");
;   MM(5, xf5)
;   asm volatile("s_waitcnt lgkmcnt(1)" : "+v"(xf6) : : "memory");
;   MM(6, xf6)
;   asm volatile("s_waitcnt lgkmcnt(0)" : "+v"(xf7) : : "memory");
;   MM(7, xf7)
;     ...
; }
; template <class F>
; __device__ __forceinline__ void gemm_big(const ALbf& al, const u16* __restrict__ Wt, int K, int m0, int n0, const F& f, u16* sm) {
;     ...
;   for (int kt = 0; kt < nk; ++kt) {
;     const int nxt2 = (cur >= 1) ? cur - 1 : 2;
;     gb_step(ga, gw, a64, w64, (kt + 2) * 32, kt + 2 < nk, sm + cur * GB_STAGE_EL, sm + nxt2 * GB_STAGE_EL, wave, wm, wn, lane, rsw, acc);
.Lgz3_mloop:
	v_add_u32_e32 v212, s12, v216
	ds_read_b128 v[252:255], v212 offset:0
	ds_read_b128 v[204:207], v212 offset:512
	ds_read_b128 v[208:211], v212 offset:4096
	ds_read_b128 v[212:215], v212 offset:4608
	v_mfma_f32_16x16x32_bf16 v[124:127], v[236:239], v[144:147], v[124:127]
	ds_read_b128 v[176:179], v219 offset:49152
	v_mfma_f32_16x16x32_bf16 v[120:123], v[240:243], v[144:147], v[120:123]
	ds_read_b128 v[180:183], v219 offset:51200
	v_mfma_f32_16x16x32_bf16 v[84:87], v[244:247], v[144:147], v[84:87]
	ds_read_b128 v[184:187], v219 offset:53248
	v_mfma_f32_16x16x32_bf16 v[80:83], v[248:251], v[144:147], v[80:83]
	ds_read_b128 v[188:191], v219 offset:55296
	v_mfma_f32_16x16x32_bf16 v[116:119], v[236:239], v[148:151], v[116:119]
	ds_read_b128 v[192:195], v228 offset:49152
	v_mfma_f32_16x16x32_bf16 v[112:115], v[240:243], v[148:151], v[112:115]
	ds_read_b128 v[220:223], v228 offset:51200
	v_mfma_f32_16x16x32_bf16 v[76:79], v[244:247], v[148:151], v[76:79]
	ds_read_b128 v[224:227], v228 offset:53248
	v_mfma_f32_16x16x32_bf16 v[68:71], v[248:251], v[148:151], v[68:71]
	ds_read_b128 v[232:235], v228 offset:55296
	s_add_u32 m0, s61, 0x8000
	v_mfma_f32_16x16x32_bf16 v[108:111], v[236:239], v[152:155], v[108:111]
	global_load_lds_dwordx4 v128, s[6:7]
	v_mfma_f32_16x16x32_bf16 v[104:107], v[240:243], v[152:155], v[104:107]
	s_add_u32 m0, s61, 0x9000
	v_mfma_f32_16x16x32_bf16 v[60:63], v[244:247], v[152:155], v[60:63]
	global_load_lds_dwordx4 v129, s[6:7]
	v_mfma_f32_16x16x32_bf16 v[56:59], v[248:251], v[152:155], v[56:59]
	s_add_u32 m0, s61, 0xa000
	v_mfma_f32_16x16x32_bf16 v[100:103], v[236:239], v[156:159], v[100:103]
	global_load_lds_dwordx4 v130, s[6:7]
	v_mfma_f32_16x16x32_bf16 v[96:99], v[240:243], v[156:159], v[96:99]
	s_add_u32 m0, s61, 0xb000
	v_mfma_f32_16x16x32_bf16 v[44:47], v[244:247], v[156:159], v[44:47]
	global_load_lds_dwordx4 v131, s[6:7]
	v_mfma_f32_16x16x32_bf16 v[40:43], v[248:251], v[156:159], v[40:43]
	s_waitcnt lgkmcnt(8)
	v_mfma_f32_16x16x32_bf16 v[124:127], v[252:255], v[160:163], v[124:127]
	v_mfma_f32_16x16x32_bf16 v[120:123], v[204:207], v[160:163], v[120:123]
	v_mfma_f32_16x16x32_bf16 v[84:87], v[208:211], v[160:163], v[84:87]
	v_mfma_f32_16x16x32_bf16 v[80:83], v[212:215], v[160:163], v[80:83]
	v_mfma_f32_16x16x32_bf16 v[116:119], v[252:255], v[164:167], v[116:119]
	v_mfma_f32_16x16x32_bf16 v[112:115], v[204:207], v[164:167], v[112:115]
	v_mfma_f32_16x16x32_bf16 v[76:79], v[208:211], v[164:167], v[76:79]
	v_mfma_f32_16x16x32_bf16 v[68:71], v[212:215], v[164:167], v[68:71]
	v_mfma_f32_16x16x32_bf16 v[108:111], v[252:255], v[168:171], v[108:111]
	v_mfma_f32_16x16x32_bf16 v[104:107], v[204:207], v[168:171], v[104:107]
	v_mfma_f32_16x16x32_bf16 v[60:63], v[208:211], v[168:171], v[60:63]
	v_mfma_f32_16x16x32_bf16 v[56:59], v[212:215], v[168:171], v[56:59]
	v_mfma_f32_16x16x32_bf16 v[100:103], v[252:255], v[172:175], v[100:103]
	v_mfma_f32_16x16x32_bf16 v[96:99], v[204:207], v[172:175], v[96:99]
	v_mfma_f32_16x16x32_bf16 v[44:47], v[208:211], v[172:175], v[44:47]
	v_mfma_f32_16x16x32_bf16 v[40:43], v[212:215], v[172:175], v[40:43]
	s_waitcnt vmcnt(0)
	s_waitcnt lgkmcnt(0)
	s_add_u32 s6, s6, 0x20000
	s_addc_u32 s7, s7, 0
	s_xor_b32 s13, s12, 0x4000
	s_barrier
	v_mfma_f32_16x16x32_bf16 v[92:95], v[236:239], v[176:179], v[92:95]
	ds_read_b128 v[144:147], v219 offset:32768
	v_mfma_f32_16x16x32_bf16 v[88:91], v[240:243], v[176:179], v[88:91]
	ds_read_b128 v[148:151], v219 offset:34816
	v_mfma_f32_16x16x32_bf16 v[28:31], v[244:247], v[176:179], v[28:31]
	ds_read_b128 v[152:155], v219 offset:36864
	v_mfma_f32_16x16x32_bf16 v[24:27], v[248:251], v[176:179], v[24:27]
	ds_read_b128 v[156:159], v219 offset:38912
	v_mfma_f32_16x16x32_bf16 v[72:75], v[236:239], v[180:183], v[72:75]
	ds_read_b128 v[160:163], v228 offset:32768
	v_mfma_f32_16x16x32_bf16 v[64:67], v[240:243], v[180:183], v[64:67]
	ds_read_b128 v[164:167], v228 offset:34816
	v_mfma_f32_16x16x32_bf16 v[20:23], v[244:247], v[180:183], v[20:23]
	ds_read_b128 v[168:171], v228 offset:36864
	v_mfma_f32_16x16x32_bf16 v[16:19], v[248:251], v[180:183], v[16:19]
	ds_read_b128 v[172:175], v228 offset:38912
	s_add_u32 m0, s61, 0xc000
	v_mfma_f32_16x16x32_bf16 v[52:55], v[236:239], v[184:187], v[52:55]
	global_load_lds_dwordx4 v128, s[6:7]
	v_mfma_f32_16x16x32_bf16 v[48:51], v[240:243], v[184:187], v[48:51]
	s_add_u32 m0, s61, 0xd000
	v_mfma_f32_16x16x32_bf16 v[12:15], v[244:247], v[184:187], v[12:15]
	global_load_lds_dwordx4 v129, s[6:7]
	v_mfma_f32_16x16x32_bf16 v[8:11], v[248:251], v[184:187], v[8:11]
	s_add_u32 m0, s61, 0xe000
	v_mfma_f32_16x16x32_bf16 v[36:39], v[236:239], v[188:191], v[36:39]
	global_load_lds_dwordx4 v130, s[6:7]
	v_mfma_f32_16x16x32_bf16 v[32:35], v[240:243], v[188:191], v[32:35]
	s_add_u32 m0, s61, 0xf000
	v_mfma_f32_16x16x32_bf16 v[4:7], v[244:247], v[188:191], v[4:7]
	global_load_lds_dwordx4 v131, s[6:7]
	v_mfma_f32_16x16x32_bf16 v[0:3], v[248:251], v[188:191], v[0:3]
	v_add_u32_e32 v248, s13, v231
	v_mfma_f32_16x16x32_bf16 v[92:95], v[252:255], v[192:195], v[92:95]
	ds_read_b128 v[236:239], v248 offset:0
	v_mfma_f32_16x16x32_bf16 v[88:91], v[204:207], v[192:195], v[88:91]
	ds_read_b128 v[240:243], v248 offset:512
	v_mfma_f32_16x16x32_bf16 v[28:31], v[208:211], v[192:195], v[28:31]
	ds_read_b128 v[244:247], v248 offset:4096
	v_mfma_f32_16x16x32_bf16 v[24:27], v[212:215], v[192:195], v[24:27]
	ds_read_b128 v[248:251], v248 offset:4608
	v_mfma_f32_16x16x32_bf16 v[72:75], v[252:255], v[220:223], v[72:75]
	v_mfma_f32_16x16x32_bf16 v[64:67], v[204:207], v[220:223], v[64:67]
	s_add_u32 m0, s61, s12
	s_add_u32 m0, m0, 0x0
	s_nop 0
	global_load_lds_dwordx4 v134, s[10:11]
	v_mfma_f32_16x16x32_bf16 v[20:23], v[208:211], v[220:223], v[20:23]
	v_mfma_f32_16x16x32_bf16 v[16:19], v[212:215], v[220:223], v[16:19]
	s_add_u32 m0, s61, s12
	s_add_u32 m0, m0, 0x1000
	s_nop 0
	global_load_lds_dwordx4 v143, s[10:11]
	v_mfma_f32_16x16x32_bf16 v[52:55], v[252:255], v[224:227], v[52:55]
	v_mfma_f32_16x16x32_bf16 v[48:51], v[204:207], v[224:227], v[48:51]
	s_add_u32 m0, s61, s12
	s_add_u32 m0, m0, 0x2000
	s_nop 0
	global_load_lds_dwordx4 v196, s[10:11]
	v_mfma_f32_16x16x32_bf16 v[12:15], v[208:211], v[224:227], v[12:15]
	v_mfma_f32_16x16x32_bf16 v[8:11], v[212:215], v[224:227], v[8:11]
	s_add_u32 m0, s61, s12
	s_add_u32 m0, m0, 0x3000
	s_nop 0
	global_load_lds_dwordx4 v197, s[10:11]
	v_mfma_f32_16x16x32_bf16 v[36:39], v[252:255], v[232:235], v[36:39]
	v_mfma_f32_16x16x32_bf16 v[32:35], v[204:207], v[232:235], v[32:35]
	v_mfma_f32_16x16x32_bf16 v[4:7], v[208:211], v[232:235], v[4:7]
	v_mfma_f32_16x16x32_bf16 v[0:3], v[212:215], v[232:235], v[0:3]
	s_waitcnt vmcnt(4)
	s_waitcnt lgkmcnt(0)
	s_add_u32 s6, s6, 0xfffe0080
	s_addc_u32 s7, s7, -1
	s_add_u32 s10, s10, 0x80
	s_addc_u32 s11, s11, 0
	s_mov_b32 s12, s13
	s_add_u32 s60, s60, 1
	s_cmp_lt_u32 s60, 14
	s_barrier
	s_cbranch_scc1 .Lgz3_mloop

; __device__ __forceinline__ void gb_step(const u16* ga, const u16* gw, size_t a64, size_t w64, int ko, bool issue, ...
;   if (issue) {
; #pragma unroll
;     for (int i = 0; i < 4; i++)
;       __builtin_amdgcn_global_load_lds((const unsigned*)(ga + i * a64 + ko), (lds_u32*)(wr + (i * 4 + wave) * 512), 16, 0, 0);
; #pragma unroll
;     for (int i = 0; i < 2; i++)
;       __builtin_amdgcn_global_load_lds((const unsigned*)(gw + i * w64 + ko), (lds_u32*)(wr + 256 * GST + (i * 4 + wave) * 512), 16, 0, 0);
;   }
;   const unsigned rdb = (unsigned)(size_t)(__attribute__((address_space(3))) const char*)rd;
;   const unsigned ab = rdb + (unsigned)(((wm * 128 + (lane & 15)) * GST + rsw) * 2);
;   const int wr0 = wn * 64 + (((lane & 15) >> 2) << 3) + (lane & 3);
;   const unsigned bb0 = rdb + (unsigned)((256 * GST + wr0 * GST + GSW(wr0, lane >> 4)) * 2);
;   const unsigned bb1 = rdb + (unsigned)((256 * GST + (wr0 + 4) * GST + GSW(wr0 + 4, lane >> 4)) * 2);
;   bf16x8 wf0, wf1, wf2, wf3, xf0, xf1, xf2, xf3, xf4, xf5, xf6, xf7;
;     ...
;   DSR(wf0, bb0, 0); DSR(wf1, bb1, 0); DSR(wf2, bb0, 2048); DSR(wf3, bb1, 2048);
;   DSR(xf0, ab, 0); DSR(xf1, ab, 1024); DSR(xf2, ab, 2048); DSR(xf3, ab, 3072);
;   DSR(xf4, ab, 4096); DSR(xf5, ab, 5120); DSR(xf6, ab, 6144); DSR(xf7, ab, 7168);
;     ...
;   asm volatile("s_waitcnt lgkmcnt(7)" : "+v"(wf0), "+v"(wf1), "+v"(wf2), "+v"(wf3), "+v"(xf0) : : "memory");
;   MM(0, xf0)
;   asm volatile("s_waitcnt lgkmcnt(6)" : "+v"(xf1) : : "memory");
;   MM(1, xf1)
;   asm volatile("s_waitcnt lgkmcnt(5)" : "+v"(xf2) : : "memory");
;   MM(2, xf2)
;   asm volatile("s_waitcnt lgkmcnt(4)" : "+v"(xf3) : : "memory");
;   MM(3, xf3)
;   asm volatile("s_waitcnt lgkmcnt(3)" : "+v"(xf4) : : "memory");
;   MM(4, xf4)
;   asm volatile("s_waitcnt lgkmcnt(2)" : "+v"(xf5) : : "memory");
;   MM(5, xf5)
;   asm volatile("s_waitcnt lgkmcnt(1)" : "+v"(xf6) : : "memory");
;   MM(6, xf6)
;   asm volatile("s_waitcnt lgkmcnt(0)" : "+v"(xf7) : : "memory");
;   MM(7, xf7)
;     ...
; }
; template <class F>
; __device__ __forceinline__ void gemm_big(const ALbf& al, const u16* __restrict__ Wt, int K, int m0, int n0, const F& f, u16* sm) {
;     ...
;   for (int kt = 0; kt < nk; ++kt) {
;     const int nxt2 = (cur >= 1) ? cur - 1 : 2;
;     gb_step(ga, gw, a64, w64, (kt + 2) * 32, kt + 2 < nk, sm + cur * GB_STAGE_EL, sm + nxt2 * GB_STAGE_EL, wave, wm, wn, lane, rsw, acc);
.Lgz4_mloop:
	v_add_u32_e32 v212, s10, v216
	ds_read_b128 v[252:255], v212 offset:0
	ds_read_b128 v[204:207], v212 offset:512
	ds_read_b128 v[208:211], v212 offset:4096
	ds_read_b128 v[212:215], v212 offset:4608
	v_mfma_f32_16x16x32_bf16 v[124:127], v[236:239], v[144:147], v[124:127]
	ds_read_b128 v[176:179], v219 offset:49152
	v_mfma_f32_16x16x32_bf16 v[120:123], v[240:243], v[144:147], v[120:123]
	ds_read_b128 v[180:183], v219 offset:51200
	v_mfma_f32_16x16x32_bf16 v[84:87], v[244:247], v[144:147], v[84:87]
	ds_read_b128 v[184:187], v219 offset:53248
	v_mfma_f32_16x16x32_bf16 v[80:83], v[248:251], v[144:147], v[80:83]
	ds_read_b128 v[188:191], v219 offset:55296
	v_mfma_f32_16x16x32_bf16 v[116:119], v[236:239], v[148:151], v[116:119]
	ds_read_b128 v[192:195], v228 offset:49152
	v_mfma_f32_16x16x32_bf16 v[112:115], v[240:243], v[148:151], v[112:115]
	ds_read_b128 v[220:223], v228 offset:51200
	v_mfma_f32_16x16x32_bf16 v[76:79], v[244:247], v[148:151], v[76:79]
	ds_read_b128 v[224:227], v228 offset:53248
	v_mfma_f32_16x16x32_bf16 v[68:71], v[248:251], v[148:151], v[68:71]
	ds_read_b128 v[232:235], v228 offset:55296
	s_add_u32 m0, s17, 0x8000
	v_mfma_f32_16x16x32_bf16 v[108:111], v[236:239], v[152:155], v[108:111]
	global_load_lds_dwordx4 v128, s[6:7]
	v_mfma_f32_16x16x32_bf16 v[104:107], v[240:243], v[152:155], v[104:107]
	s_add_u32 m0, s17, 0x9000
	v_mfma_f32_16x16x32_bf16 v[60:63], v[244:247], v[152:155], v[60:63]
	global_load_lds_dwordx4 v129, s[6:7]
	v_mfma_f32_16x16x32_bf16 v[56:59], v[248:251], v[152:155], v[56:59]
	s_add_u32 m0, s17, 0xa000
	v_mfma_f32_16x16x32_bf16 v[100:103], v[236:239], v[156:159], v[100:103]
	global_load_lds_dwordx4 v130, s[6:7]
	v_mfma_f32_16x16x32_bf16 v[96:99], v[240:243], v[156:159], v[96:99]
	s_add_u32 m0, s17, 0xb000
	v_mfma_f32_16x16x32_bf16 v[44:47], v[244:247], v[156:159], v[44:47]
	global_load_lds_dwordx4 v131, s[6:7]
	v_mfma_f32_16x16x32_bf16 v[40:43], v[248:251], v[156:159], v[40:43]
	s_waitcnt lgkmcnt(8)
	v_mfma_f32_16x16x32_bf16 v[124:127], v[252:255], v[160:163], v[124:127]
	v_mfma_f32_16x16x32_bf16 v[120:123], v[204:207], v[160:163], v[120:123]
	v_mfma_f32_16x16x32_bf16 v[84:87], v[208:211], v[160:163], v[84:87]
	v_mfma_f32_16x16x32_bf16 v[80:83], v[212:215], v[160:163], v[80:83]
	v_mfma_f32_16x16x32_bf16 v[116:119], v[252:255], v[164:167], v[116:119]
	v_mfma_f32_16x16x32_bf16 v[112:115], v[204:207], v[164:167], v[112:115]
	v_mfma_f32_16x16x32_bf16 v[76:79], v[208:211], v[164:167], v[76:79]
	v_mfma_f32_16x16x32_bf16 v[68:71], v[212:215], v[164:167], v[68:71]
	v_mfma_f32_16x16x32_bf16 v[108:111], v[252:255], v[168:171], v[108:111]
	v_mfma_f32_16x16x32_bf16 v[104:107], v[204:207], v[168:171], v[104:107]
	v_mfma_f32_16x16x32_bf16 v[60:63], v[208:211], v[168:171], v[60:63]
	v_mfma_f32_16x16x32_bf16 v[56:59], v[212:215], v[168:171], v[56:59]
	v_mfma_f32_16x16x32_bf16 v[100:103], v[252:255], v[172:175], v[100:103]
	v_mfma_f32_16x16x32_bf16 v[96:99], v[204:207], v[172:175], v[96:99]
	v_mfma_f32_16x16x32_bf16 v[44:47], v[208:211], v[172:175], v[44:47]
	v_mfma_f32_16x16x32_bf16 v[40:43], v[212:215], v[172:175], v[40:43]
	s_waitcnt vmcnt(0)
	s_waitcnt lgkmcnt(0)
	s_add_u32 s6, s6, 0x20000
	s_addc_u32 s7, s7, 0
	s_xor_b32 s11, s10, 0x4000
	s_barrier
	v_mfma_f32_16x16x32_bf16 v[92:95], v[236:239], v[176:179], v[92:95]
	ds_read_b128 v[144:147], v219 offset:32768
	v_mfma_f32_16x16x32_bf16 v[88:91], v[240:243], v[176:179], v[88:91]
	ds_read_b128 v[148:151], v219 offset:34816
	v_mfma_f32_16x16x32_bf16 v[28:31], v[244:247], v[176:179], v[28:31]
	ds_read_b128 v[152:155], v219 offset:36864
	v_mfma_f32_16x16x32_bf16 v[24:27], v[248:251], v[176:179], v[24:27]
	ds_read_b128 v[156:159], v219 offset:38912
	v_mfma_f32_16x16x32_bf16 v[72:75], v[236:239], v[180:183], v[72:75]
	ds_read_b128 v[160:163], v228 offset:32768
	v_mfma_f32_16x16x32_bf16 v[64:67], v[240:243], v[180:183], v[64:67]
	ds_read_b128 v[164:167], v228 offset:34816
	v_mfma_f32_16x16x32_bf16 v[20:23], v[244:247], v[180:183], v[20:23]
	ds_read_b128 v[168:171], v228 offset:36864
	v_mfma_f32_16x16x32_bf16 v[16:19], v[248:251], v[180:183], v[16:19]
	ds_read_b128 v[172:175], v228 offset:38912
	s_add_u32 m0, s17, 0xc000
	v_mfma_f32_16x16x32_bf16 v[52:55], v[236:239], v[184:187], v[52:55]
	global_load_lds_dwordx4 v128, s[6:7]
	v_mfma_f32_16x16x32_bf16 v[48:51], v[240:243], v[184:187], v[48:51]
	s_add_u32 m0, s17, 0xd000
	v_mfma_f32_16x16x32_bf16 v[12:15], v[244:247], v[184:187], v[12:15]
	global_load_lds_dwordx4 v129, s[6:7]
	v_mfma_f32_16x16x32_bf16 v[8:11], v[248:251], v[184:187], v[8:11]
	s_add_u32 m0, s17, 0xe000
	v_mfma_f32_16x16x32_bf16 v[36:39], v[236:239], v[188:191], v[36:39]
	global_load_lds_dwordx4 v130, s[6:7]
	v_mfma_f32_16x16x32_bf16 v[32:35], v[240:243], v[188:191], v[32:35]
	s_add_u32 m0, s17, 0xf000
	v_mfma_f32_16x16x32_bf16 v[4:7], v[244:247], v[188:191], v[4:7]
	global_load_lds_dwordx4 v131, s[6:7]
	v_mfma_f32_16x16x32_bf16 v[0:3], v[248:251], v[188:191], v[0:3]
	v_add_u32_e32 v248, s11, v231
	v_mfma_f32_16x16x32_bf16 v[92:95], v[252:255], v[192:195], v[92:95]
	ds_read_b128 v[236:239], v248 offset:0
	v_mfma_f32_16x16x32_bf16 v[88:91], v[204:207], v[192:195], v[88:91]
	ds_read_b128 v[240:243], v248 offset:512
	v_mfma_f32_16x16x32_bf16 v[28:31], v[208:211], v[192:195], v[28:31]
	ds_read_b128 v[244:247], v248 offset:4096
	v_mfma_f32_16x16x32_bf16 v[24:27], v[212:215], v[192:195], v[24:27]
	ds_read_b128 v[248:251], v248 offset:4608
	v_mfma_f32_16x16x32_bf16 v[72:75], v[252:255], v[220:223], v[72:75]
	v_mfma_f32_16x16x32_bf16 v[64:67], v[204:207], v[220:223], v[64:67]
	s_add_u32 m0, s17, s10
	s_add_u32 m0, m0, 0x0
	s_nop 0
	global_load_lds_dwordx4 v134, s[8:9]
	v_mfma_f32_16x16x32_bf16 v[20:23], v[208:211], v[220:223], v[20:23]
	v_mfma_f32_16x16x32_bf16 v[16:19], v[212:215], v[220:223], v[16:19]
	s_add_u32 m0, s17, s10
	s_add_u32 m0, m0, 0x1000
	s_nop 0
	global_load_lds_dwordx4 v143, s[8:9]
	v_mfma_f32_16x16x32_bf16 v[52:55], v[252:255], v[224:227], v[52:55]
	v_mfma_f32_16x16x32_bf16 v[48:51], v[204:207], v[224:227], v[48:51]
	s_add_u32 m0, s17, s10
	s_add_u32 m0, m0, 0x2000
	s_nop 0
	global_load_lds_dwordx4 v196, s[8:9]
	v_mfma_f32_16x16x32_bf16 v[12:15], v[208:211], v[224:227], v[12:15]
	v_mfma_f32_16x16x32_bf16 v[8:11], v[212:215], v[224:227], v[8:11]
	s_add_u32 m0, s17, s10
	s_add_u32 m0, m0, 0x3000
	s_nop 0
	global_load_lds_dwordx4 v197, s[8:9]
	v_mfma_f32_16x16x32_bf16 v[36:39], v[252:255], v[232:235], v[36:39]
	v_mfma_f32_16x16x32_bf16 v[32:35], v[204:207], v[232:235], v[32:35]
	v_mfma_f32_16x16x32_bf16 v[4:7], v[208:211], v[232:235], v[4:7]
	v_mfma_f32_16x16x32_bf16 v[0:3], v[212:215], v[232:235], v[0:3]
	s_waitcnt vmcnt(4)
	s_waitcnt lgkmcnt(0)
	s_add_u32 s6, s6, 0xfffe0080
	s_addc_u32 s7, s7, -1
	s_add_u32 s8, s8, 0x80
	s_addc_u32 s9, s9, 0
	s_mov_b32 s10, s11
	s_add_u32 s16, s16, 1
	s_cmp_lt_u32 s16, 14
	s_barrier
	s_cbranch_scc1 .Lgz4_mloop

; __device__ __forceinline__ void gb_step(const u16* ga, const u16* gw, size_t a64, size_t w64, int ko, bool issue, ...
;   if (issue) {
; #pragma unroll
;     for (int i = 0; i < 4; i++)
;       __builtin_amdgcn_global_load_lds((const unsigned*)(ga + i * a64 + ko), (lds_u32*)(wr + (i * 4 + wave) * 512), 16, 0, 0);
; #pragma unroll
;     for (int i = 0; i < 2; i++)
;       __builtin_amdgcn_global_load_lds((const unsigned*)(gw + i * w64 + ko), (lds_u32*)(wr + 256 * GST + (i * 4 + wave) * 512), 16, 0, 0);
;   }
;   const unsigned rdb = (unsigned)(size_t)(__attribute__((address_space(3))) const char*)rd;
;   const unsigned ab = rdb + (unsigned)(((wm * 128 + (lane & 15)) * GST + rsw) * 2);
;   const int wr0 = wn * 64 + (((lane & 15) >> 2) << 3) + (lane & 3);
;   const unsigned bb0 = rdb + (unsigned)((256 * GST + wr0 * GST + GSW(wr0, lane >> 4)) * 2);
;   const unsigned bb1 = rdb + (unsigned)((256 * GST + (wr0 + 4) * GST + GSW(wr0 + 4, lane >> 4)) * 2);
;   bf16x8 wf0, wf1, wf2, wf3, xf0, xf1, xf2, xf3, xf4, xf5, xf6, xf7;
;     ...
;   DSR(wf0, bb0, 0); DSR(wf1, bb1, 0); DSR(wf2, bb0, 2048); DSR(wf3, bb1, 2048);
;   DSR(xf0, ab, 0); DSR(xf1, ab, 1024); DSR(xf2, ab, 2048); DSR(xf3, ab, 3072);
;   DSR(xf4, ab, 4096); DSR(xf5, ab, 5120); DSR(xf6, ab, 6144); DSR(xf7, ab, 7168);
;     ...
;   asm volatile("s_waitcnt lgkmcnt(7)" : "+v"(wf0), "+v"(wf1), "+v"(wf2), "+v"(wf3), "+v"(xf0) : : "memory");
;   MM(0, xf0)
;   asm volatile("s_waitcnt lgkmcnt(6)" : "+v"(xf1) : : "memory");
;   MM(1, xf1)
;   asm volatile("s_waitcnt lgkmcnt(5)" : "+v"(xf2) : : "memory");
;   MM(2, xf2)
;   asm volatile("s_waitcnt lgkmcnt(4)" : "+v"(xf3) : : "memory");
;   MM(3, xf3)
;   asm volatile("s_waitcnt lgkmcnt(3)" : "+v"(xf4) : : "memory");
;   MM(4, xf4)
;   asm volatile("s_waitcnt lgkmcnt(2)" : "+v"(xf5) : : "memory");
;   MM(5, xf5)
;   asm volatile("s_waitcnt lgkmcnt(1)" : "+v"(xf6) : : "memory");
;   MM(6, xf6)
;   asm volatile("s_waitcnt lgkmcnt(0)" : "+v"(xf7) : : "memory");
;   MM(7, xf7)
;     ...
; }
; template <class F>
; __device__ __forceinline__ void gemm_big(const ALbf& al, const u16* __restrict__ Wt, int K, int m0, int n0, const F& f, u16* sm) {
;     ...
;   for (int kt = 0; kt < nk; ++kt) {
;     const int nxt2 = (cur >= 1) ? cur - 1 : 2;
;     gb_step(ga, gw, a64, w64, (kt + 2) * 32, kt + 2 < nk, sm + cur * GB_STAGE_EL, sm + nxt2 * GB_STAGE_EL, wave, wm, wn, lane, rsw, acc);
.Lgz5_mloop:
	v_add_u32_e32 v212, s16, v216
	ds_read_b128 v[252:255], v212 offset:0
	ds_read_b128 v[204:207], v212 offset:512
	ds_read_b128 v[208:211], v212 offset:4096
	ds_read_b128 v[212:215], v212 offset:4608
	v_mfma_f32_16x16x32_bf16 v[124:127], v[236:239], v[144:147], v[124:127]
	ds_read_b128 v[176:179], v219 offset:49152
	v_mfma_f32_16x16x32_bf16 v[120:123], v[240:243], v[144:147], v[120:123]
	ds_read_b128 v[180:183], v219 offset:51200
	v_mfma_f32_16x16x32_bf16 v[84:87], v[244:247], v[144:147], v[84:87]
	ds_read_b128 v[184:187], v219 offset:53248
	v_mfma_f32_16x16x32_bf16 v[80:83], v[248:251], v[144:147], v[80:83]
	ds_read_b128 v[188:191], v219 offset:55296
	v_mfma_f32_16x16x32_bf16 v[116:119], v[236:239], v[148:151], v[116:119]
	ds_read_b128 v[192:195], v228 offset:49152
	v_mfma_f32_16x16x32_bf16 v[112:115], v[240:243], v[148:151], v[112:115]
	ds_read_b128 v[220:223], v228 offset:51200
	v_mfma_f32_16x16x32_bf16 v[76:79], v[244:247], v[148:151], v[76:79]
	ds_read_b128 v[224:227], v228 offset:53248
	v_mfma_f32_16x16x32_bf16 v[68:71], v[248:251], v[148:151], v[68:71]
	ds_read_b128 v[232:235], v228 offset:55296
	s_add_u32 m0, s94, 0x8000
	v_mfma_f32_16x16x32_bf16 v[108:111], v[236:239], v[152:155], v[108:111]
	global_load_lds_dwordx4 v128, s[10:11]
	v_mfma_f32_16x16x32_bf16 v[104:107], v[240:243], v[152:155], v[104:107]
	s_add_u32 m0, s94, 0x9000
	v_mfma_f32_16x16x32_bf16 v[60:63], v[244:247], v[152:155], v[60:63]
	global_load_lds_dwordx4 v129, s[10:11]
	v_mfma_f32_16x16x32_bf16 v[56:59], v[248:251], v[152:155], v[56:59]
	s_add_u32 m0, s94, 0xa000
	v_mfma_f32_16x16x32_bf16 v[100:103], v[236:239], v[156:159], v[100:103]
	global_load_lds_dwordx4 v130, s[10:11]
	v_mfma_f32_16x16x32_bf16 v[96:99], v[240:243], v[156:159], v[96:99]
	s_add_u32 m0, s94, 0xb000
	v_mfma_f32_16x16x32_bf16 v[44:47], v[244:247], v[156:159], v[44:47]
	global_load_lds_dwordx4 v131, s[10:11]
	v_mfma_f32_16x16x32_bf16 v[40:43], v[248:251], v[156:159], v[40:43]
	s_waitcnt lgkmcnt(8)
	v_mfma_f32_16x16x32_bf16 v[124:127], v[252:255], v[160:163], v[124:127]
	v_mfma_f32_16x16x32_bf16 v[120:123], v[204:207], v[160:163], v[120:123]
	v_mfma_f32_16x16x32_bf16 v[84:87], v[208:211], v[160:163], v[84:87]
	v_mfma_f32_16x16x32_bf16 v[80:83], v[212:215], v[160:163], v[80:83]
	v_mfma_f32_16x16x32_bf16 v[116:119], v[252:255], v[164:167], v[116:119]
	v_mfma_f32_16x16x32_bf16 v[112:115], v[204:207], v[164:167], v[112:115]
	v_mfma_f32_16x16x32_bf16 v[76:79], v[208:211], v[164:167], v[76:79]
	v_mfma_f32_16x16x32_bf16 v[68:71], v[212:215], v[164:167], v[68:71]
	v_mfma_f32_16x16x32_bf16 v[108:111], v[252:255], v[168:171], v[108:111]
	v_mfma_f32_16x16x32_bf16 v[104:107], v[204:207], v[168:171], v[104:107]
	v_mfma_f32_16x16x32_bf16 v[60:63], v[208:211], v[168:171], v[60:63]
	v_mfma_f32_16x16x32_bf16 v[56:59], v[212:215], v[168:171], v[56:59]
	v_mfma_f32_16x16x32_bf16 v[100:103], v[252:255], v[172:175], v[100:103]
	v_mfma_f32_16x16x32_bf16 v[96:99], v[204:207], v[172:175], v[96:99]
	v_mfma_f32_16x16x32_bf16 v[44:47], v[208:211], v[172:175], v[44:47]
	v_mfma_f32_16x16x32_bf16 v[40:43], v[212:215], v[172:175], v[40:43]
	s_waitcnt vmcnt(0)
	s_waitcnt lgkmcnt(0)
	s_add_u32 s10, s10, 0x20000
	s_addc_u32 s11, s11, 0
	s_xor_b32 s17, s16, 0x4000
	s_barrier
	v_mfma_f32_16x16x32_bf16 v[92:95], v[236:239], v[176:179], v[92:95]
	ds_read_b128 v[144:147], v219 offset:32768
	v_mfma_f32_16x16x32_bf16 v[88:91], v[240:243], v[176:179], v[88:91]
	ds_read_b128 v[148:151], v219 offset:34816
	v_mfma_f32_16x16x32_bf16 v[28:31], v[244:247], v[176:179], v[28:31]
	ds_read_b128 v[152:155], v219 offset:36864
	v_mfma_f32_16x16x32_bf16 v[24:27], v[248:251], v[176:179], v[24:27]
	ds_read_b128 v[156:159], v219 offset:38912
	v_mfma_f32_16x16x32_bf16 v[72:75], v[236:239], v[180:183], v[72:75]
	ds_read_b128 v[160:163], v228 offset:32768
	v_mfma_f32_16x16x32_bf16 v[64:67], v[240:243], v[180:183], v[64:67]
	ds_read_b128 v[164:167], v228 offset:34816
	v_mfma_f32_16x16x32_bf16 v[20:23], v[244:247], v[180:183], v[20:23]
	ds_read_b128 v[168:171], v228 offset:36864
	v_mfma_f32_16x16x32_bf16 v[16:19], v[248:251], v[180:183], v[16:19]
	ds_read_b128 v[172:175], v228 offset:38912
	s_add_u32 m0, s94, 0xc000
	v_mfma_f32_16x16x32_bf16 v[52:55], v[236:239], v[184:187], v[52:55]
	global_load_lds_dwordx4 v128, s[10:11]
	v_mfma_f32_16x16x32_bf16 v[48:51], v[240:243], v[184:187], v[48:51]
	s_add_u32 m0, s94, 0xd000
	v_mfma_f32_16x16x32_bf16 v[12:15], v[244:247], v[184:187], v[12:15]
	global_load_lds_dwordx4 v129, s[10:11]
	v_mfma_f32_16x16x32_bf16 v[8:11], v[248:251], v[184:187], v[8:11]
	s_add_u32 m0, s94, 0xe000
	v_mfma_f32_16x16x32_bf16 v[36:39], v[236:239], v[188:191], v[36:39]
	global_load_lds_dwordx4 v130, s[10:11]
	v_mfma_f32_16x16x32_bf16 v[32:35], v[240:243], v[188:191], v[32:35]
	s_add_u32 m0, s94, 0xf000
	v_mfma_f32_16x16x32_bf16 v[4:7], v[244:247], v[188:191], v[4:7]
	global_load_lds_dwordx4 v131, s[10:11]
	v_mfma_f32_16x16x32_bf16 v[0:3], v[248:251], v[188:191], v[0:3]
	v_add_u32_e32 v248, s17, v231
	v_mfma_f32_16x16x32_bf16 v[92:95], v[252:255], v[192:195], v[92:95]
	ds_read_b128 v[236:239], v248 offset:0
	v_mfma_f32_16x16x32_bf16 v[88:91], v[204:207], v[192:195], v[88:91]
	ds_read_b128 v[240:243], v248 offset:512
	v_mfma_f32_16x16x32_bf16 v[28:31], v[208:211], v[192:195], v[28:31]
	ds_read_b128 v[244:247], v248 offset:4096
	v_mfma_f32_16x16x32_bf16 v[24:27], v[212:215], v[192:195], v[24:27]
	ds_read_b128 v[248:251], v248 offset:4608
	v_mfma_f32_16x16x32_bf16 v[72:75], v[252:255], v[220:223], v[72:75]
	v_mfma_f32_16x16x32_bf16 v[64:67], v[204:207], v[220:223], v[64:67]
	s_add_u32 m0, s94, s16
	s_add_u32 m0, m0, 0x0
	s_nop 0
	global_load_lds_dwordx4 v134, s[14:15]
	v_mfma_f32_16x16x32_bf16 v[20:23], v[208:211], v[220:223], v[20:23]
	v_mfma_f32_16x16x32_bf16 v[16:19], v[212:215], v[220:223], v[16:19]
	s_add_u32 m0, s94, s16
	s_add_u32 m0, m0, 0x1000
	s_nop 0
	global_load_lds_dwordx4 v143, s[14:15]
	v_mfma_f32_16x16x32_bf16 v[52:55], v[252:255], v[224:227], v[52:55]
	v_mfma_f32_16x16x32_bf16 v[48:51], v[204:207], v[224:227], v[48:51]
	s_add_u32 m0, s94, s16
	s_add_u32 m0, m0, 0x2000
	s_nop 0
	global_load_lds_dwordx4 v196, s[14:15]
	v_mfma_f32_16x16x32_bf16 v[12:15], v[208:211], v[224:227], v[12:15]
	v_mfma_f32_16x16x32_bf16 v[8:11], v[212:215], v[224:227], v[8:11]
	s_add_u32 m0, s94, s16
	s_add_u32 m0, m0, 0x3000
	s_nop 0
	global_load_lds_dwordx4 v197, s[14:15]
	v_mfma_f32_16x16x32_bf16 v[36:39], v[252:255], v[232:235], v[36:39]
	v_mfma_f32_16x16x32_bf16 v[32:35], v[204:207], v[232:235], v[32:35]
	v_mfma_f32_16x16x32_bf16 v[4:7], v[208:211], v[232:235], v[4:7]
	v_mfma_f32_16x16x32_bf16 v[0:3], v[212:215], v[232:235], v[0:3]
	s_waitcnt vmcnt(4)
	s_waitcnt lgkmcnt(0)
	s_add_u32 s10, s10, 0xfffe0080
	s_addc_u32 s11, s11, -1
	s_add_u32 s14, s14, 0x80
	s_addc_u32 s15, s15, 0
	s_mov_b32 s16, s17
	s_add_u32 s93, s93, 1
	s_cmp_lt_u32 s93, 14
	s_barrier
	s_cbranch_scc1 .Lgz5_mloop
